# gmlp: batched loads, rstd pass in two 8-row batches, conflict-free vnT staging via ds_write_b64; mout dir1 epilogue: O and norm-gain loads issued up front
# baseline (speedup 1.0000x reference)
; __device__ __forceinline__ float bfel(const u32x4& v, int c) { const unsigned w = (c >> 1) == 0 ? v.x : (c >> 1) == 1 ? v.y : (c >> 1) == 2 ? v.z : v.w; return (c & 1) ? bfhi(w) : bflo(w); }
; __device__ __forceinline__ void gmlp_unit(const Params& p, LAS unsigned char* lds, int unit) {
;     ...
;     for (int q = wid; q < 128; q += 8) {
;         float ss = 0.f;
; #pragma unroll
;         for (int i = 0; i < 2; ++i) { const u32x4 v = *(const u32x4*)(GV + (size_t)(r0 + q) * 1024 + i * 512 + lane * 8);
; #pragma unroll
;             for (int c = 0; c < 8; ++c) { const float f = bfel(v, c); ss += f * f; } }
;         ss = wave_sum(ss);
;         if (lane == 0) rstd[q] = rsqrtf(ss * (1.f / 1024.f) + 1e-6f);
;     }
.LBB0_1329:
	s_andn2_b64 vcc, exec, s[4:5]
	s_cbranch_vccnz .LBB0_1283
	v_and_b32_e32 v0, 64, v155
	v_add_u32_e32 v5, 64, v0
	v_xor_b32_e32 v0, 32, v155
	v_cmp_lt_i32_e32 vcc, v0, v5
	v_xor_b32_e32 v1, 16, v155
	v_xor_b32_e32 v2, 8, v155
	v_cndmask_b32_e32 v0, v155, v0, vcc
	v_cmp_lt_i32_e32 vcc, v1, v5
	v_xor_b32_e32 v3, 4, v155
	v_xor_b32_e32 v4, 2, v155
	v_cndmask_b32_e32 v1, v155, v1, vcc
	v_cmp_lt_i32_e32 vcc, v2, v5
	v_xor_b32_e32 v6, 1, v155
	v_lshlrev_b32_e32 v0, 2, v0
	v_cndmask_b32_e32 v2, v155, v2, vcc
	v_cmp_lt_i32_e32 vcc, v3, v5
	v_lshlrev_b32_e32 v1, 2, v1
	v_lshlrev_b32_e32 v2, 2, v2
	v_cndmask_b32_e32 v3, v155, v3, vcc
	v_cmp_lt_i32_e32 vcc, v4, v5
	v_lshlrev_b32_e32 v3, 2, v3
	s_mov_b64 s[4:5], 0
	v_cndmask_b32_e32 v4, v155, v4, vcc
	v_cmp_lt_i32_e32 vcc, v6, v5
	v_lshlrev_b32_e32 v4, 2, v4
	v_mov_b32_e32 v7, v138
	v_cndmask_b32_e32 v5, v155, v6, vcc
	v_lshlrev_b32_e32 v5, 2, v5
	v_mov_b32_e32 v6, v146
	v_add_u32_e32 v8, s3, v138
	v_ashrrev_i32_e32 v9, 31, v8
	v_lshlrev_b64 v[8:9], 11, v[8:9]
	v_lshl_add_u64 v[12:13], v[104:105], 0, v[8:9]
	s_mov_b64 s[80:81], 0x4000
	global_load_dwordx4 v[184:187], v[12:13], off
	global_load_dwordx4 v[188:191], v[12:13], off offset:1024
	v_lshl_add_u64 v[12:13], v[12:13], 0, s[80:81]
	global_load_dwordx4 v[192:195], v[12:13], off
	global_load_dwordx4 v[196:199], v[12:13], off offset:1024
	v_lshl_add_u64 v[12:13], v[12:13], 0, s[80:81]
	global_load_dwordx4 v[200:203], v[12:13], off
	global_load_dwordx4 v[204:207], v[12:13], off offset:1024
	v_lshl_add_u64 v[12:13], v[12:13], 0, s[80:81]
	global_load_dwordx4 v[208:211], v[12:13], off
	global_load_dwordx4 v[212:215], v[12:13], off offset:1024
	v_lshl_add_u64 v[12:13], v[12:13], 0, s[80:81]
	global_load_dwordx4 v[216:219], v[12:13], off
	global_load_dwordx4 v[220:223], v[12:13], off offset:1024
	v_lshl_add_u64 v[12:13], v[12:13], 0, s[80:81]
	global_load_dwordx4 v[224:227], v[12:13], off
	global_load_dwordx4 v[228:231], v[12:13], off offset:1024
	v_lshl_add_u64 v[12:13], v[12:13], 0, s[80:81]
	global_load_dwordx4 v[232:235], v[12:13], off
	global_load_dwordx4 v[236:239], v[12:13], off offset:1024
	v_lshl_add_u64 v[12:13], v[12:13], 0, s[80:81]
	global_load_dwordx4 v[246:249], v[12:13], off
	global_load_dwordx4 v[250:253], v[12:13], off offset:1024
	v_lshl_add_u64 v[12:13], v[12:13], 0, s[80:81]
	s_waitcnt vmcnt(14)
	v_lshlrev_b32_e32 v8, 16, v184
	v_and_b32_e32 v16, 0xffff0000, v184
	v_mul_f32_e32 v16, v16, v16
	v_fmac_f32_e32 v16, v8, v8
	v_lshlrev_b32_e32 v8, 16, v185
	v_fmac_f32_e32 v16, v8, v8
	v_and_b32_e32 v8, 0xffff0000, v185
	v_fmac_f32_e32 v16, v8, v8
	v_lshlrev_b32_e32 v8, 16, v186
	v_fmac_f32_e32 v16, v8, v8
	v_and_b32_e32 v8, 0xffff0000, v186
	v_fmac_f32_e32 v16, v8, v8
	v_lshlrev_b32_e32 v8, 16, v187
	v_fmac_f32_e32 v16, v8, v8
	v_and_b32_e32 v8, 0xffff0000, v187
	v_fmac_f32_e32 v16, v8, v8
	v_lshlrev_b32_e32 v8, 16, v188
	v_fmac_f32_e32 v16, v8, v8
	v_and_b32_e32 v8, 0xffff0000, v188
	v_fmac_f32_e32 v16, v8, v8
	v_lshlrev_b32_e32 v8, 16, v189
	v_fmac_f32_e32 v16, v8, v8
	v_and_b32_e32 v8, 0xffff0000, v189
	v_fmac_f32_e32 v16, v8, v8
	v_lshlrev_b32_e32 v8, 16, v190
	v_fmac_f32_e32 v16, v8, v8
	v_and_b32_e32 v8, 0xffff0000, v190
	v_fmac_f32_e32 v16, v8, v8
	v_lshlrev_b32_e32 v8, 16, v191
	v_fmac_f32_e32 v16, v8, v8
	v_and_b32_e32 v8, 0xffff0000, v191
	v_fmac_f32_e32 v16, v8, v8
	s_waitcnt vmcnt(12)
	v_lshlrev_b32_e32 v8, 16, v192
	v_and_b32_e32 v17, 0xffff0000, v192
	v_mul_f32_e32 v17, v17, v17
	v_fmac_f32_e32 v17, v8, v8
	v_lshlrev_b32_e32 v8, 16, v193
	v_fmac_f32_e32 v17, v8, v8
	v_and_b32_e32 v8, 0xffff0000, v193
	v_fmac_f32_e32 v17, v8, v8
	v_lshlrev_b32_e32 v8, 16, v194
	v_fmac_f32_e32 v17, v8, v8
	v_and_b32_e32 v8, 0xffff0000, v194
	v_fmac_f32_e32 v17, v8, v8
	v_lshlrev_b32_e32 v8, 16, v195
	v_fmac_f32_e32 v17, v8, v8
	v_and_b32_e32 v8, 0xffff0000, v195
	v_fmac_f32_e32 v17, v8, v8
	v_lshlrev_b32_e32 v8, 16, v196
	v_fmac_f32_e32 v17, v8, v8
	v_and_b32_e32 v8, 0xffff0000, v196
	v_fmac_f32_e32 v17, v8, v8
	v_lshlrev_b32_e32 v8, 16, v197
	v_fmac_f32_e32 v17, v8, v8
	v_and_b32_e32 v8, 0xffff0000, v197
	v_fmac_f32_e32 v17, v8, v8
	v_lshlrev_b32_e32 v8, 16, v198
	v_fmac_f32_e32 v17, v8, v8
	v_and_b32_e32 v8, 0xffff0000, v198
	v_fmac_f32_e32 v17, v8, v8
	v_lshlrev_b32_e32 v8, 16, v199
	v_fmac_f32_e32 v17, v8, v8
	v_and_b32_e32 v8, 0xffff0000, v199
	v_fmac_f32_e32 v17, v8, v8
	s_waitcnt vmcnt(10)
	v_lshlrev_b32_e32 v8, 16, v200
	v_and_b32_e32 v18, 0xffff0000, v200
	v_mul_f32_e32 v18, v18, v18
	v_fmac_f32_e32 v18, v8, v8
	v_lshlrev_b32_e32 v8, 16, v201
	v_fmac_f32_e32 v18, v8, v8
	v_and_b32_e32 v8, 0xffff0000, v201
	v_fmac_f32_e32 v18, v8, v8
	v_lshlrev_b32_e32 v8, 16, v202
	v_fmac_f32_e32 v18, v8, v8
	v_and_b32_e32 v8, 0xffff0000, v202
	v_fmac_f32_e32 v18, v8, v8
	v_lshlrev_b32_e32 v8, 16, v203
	v_fmac_f32_e32 v18, v8, v8
	v_and_b32_e32 v8, 0xffff0000, v203
	v_fmac_f32_e32 v18, v8, v8
	v_lshlrev_b32_e32 v8, 16, v204
	v_fmac_f32_e32 v18, v8, v8
	v_and_b32_e32 v8, 0xffff0000, v204
	v_fmac_f32_e32 v18, v8, v8
	v_lshlrev_b32_e32 v8, 16, v205
	v_fmac_f32_e32 v18, v8, v8
	v_and_b32_e32 v8, 0xffff0000, v205
	v_fmac_f32_e32 v18, v8, v8
	v_lshlrev_b32_e32 v8, 16, v206
	v_fmac_f32_e32 v18, v8, v8
	v_and_b32_e32 v8, 0xffff0000, v206
	v_fmac_f32_e32 v18, v8, v8
	v_lshlrev_b32_e32 v8, 16, v207
	v_fmac_f32_e32 v18, v8, v8
	v_and_b32_e32 v8, 0xffff0000, v207
	v_fmac_f32_e32 v18, v8, v8
	s_waitcnt vmcnt(8)
; __device__ __forceinline__ float bfel(const u32x4& v, int c) { const unsigned w = (c >> 1) == 0 ? v.x : (c >> 1) == 1 ? v.y : (c >> 1) == 2 ? v.z : v.w; return (c & 1) ? bfhi(w) : bflo(w); }
; __device__ __forceinline__ void gmlp_unit(const Params& p, LAS unsigned char* lds, int unit) {
;     ...
;     for (int q = wid; q < 128; q += 8) {
;         float ss = 0.f;
; #pragma unroll
;         for (int i = 0; i < 2; ++i) { const u32x4 v = *(const u32x4*)(GV + (size_t)(r0 + q) * 1024 + i * 512 + lane * 8);
; #pragma unroll
;             for (int c = 0; c < 8; ++c) { const float f = bfel(v, c); ss += f * f; } }
;         ss = wave_sum(ss);
;         if (lane == 0) rstd[q] = rsqrtf(ss * (1.f / 1024.f) + 1e-6f);
;     }
	v_lshlrev_b32_e32 v8, 16, v208
	v_and_b32_e32 v19, 0xffff0000, v208
	v_mul_f32_e32 v19, v19, v19
	v_fmac_f32_e32 v19, v8, v8
	v_lshlrev_b32_e32 v8, 16, v209
	v_fmac_f32_e32 v19, v8, v8
	v_and_b32_e32 v8, 0xffff0000, v209
	v_fmac_f32_e32 v19, v8, v8
	v_lshlrev_b32_e32 v8, 16, v210
	v_fmac_f32_e32 v19, v8, v8
	v_and_b32_e32 v8, 0xffff0000, v210
	v_fmac_f32_e32 v19, v8, v8
	v_lshlrev_b32_e32 v8, 16, v211
	v_fmac_f32_e32 v19, v8, v8
	v_and_b32_e32 v8, 0xffff0000, v211
	v_fmac_f32_e32 v19, v8, v8
	v_lshlrev_b32_e32 v8, 16, v212
	v_fmac_f32_e32 v19, v8, v8
	v_and_b32_e32 v8, 0xffff0000, v212
	v_fmac_f32_e32 v19, v8, v8
	v_lshlrev_b32_e32 v8, 16, v213
	v_fmac_f32_e32 v19, v8, v8
	v_and_b32_e32 v8, 0xffff0000, v213
	v_fmac_f32_e32 v19, v8, v8
	v_lshlrev_b32_e32 v8, 16, v214
	v_fmac_f32_e32 v19, v8, v8
	v_and_b32_e32 v8, 0xffff0000, v214
	v_fmac_f32_e32 v19, v8, v8
	v_lshlrev_b32_e32 v8, 16, v215
	v_fmac_f32_e32 v19, v8, v8
	v_and_b32_e32 v8, 0xffff0000, v215
	v_fmac_f32_e32 v19, v8, v8
	s_waitcnt vmcnt(6)
	v_lshlrev_b32_e32 v8, 16, v216
	v_and_b32_e32 v20, 0xffff0000, v216
	v_mul_f32_e32 v20, v20, v20
	v_fmac_f32_e32 v20, v8, v8
	v_lshlrev_b32_e32 v8, 16, v217
	v_fmac_f32_e32 v20, v8, v8
	v_and_b32_e32 v8, 0xffff0000, v217
	v_fmac_f32_e32 v20, v8, v8
	v_lshlrev_b32_e32 v8, 16, v218
	v_fmac_f32_e32 v20, v8, v8
	v_and_b32_e32 v8, 0xffff0000, v218
	v_fmac_f32_e32 v20, v8, v8
	v_lshlrev_b32_e32 v8, 16, v219
	v_fmac_f32_e32 v20, v8, v8
	v_and_b32_e32 v8, 0xffff0000, v219
	v_fmac_f32_e32 v20, v8, v8
	v_lshlrev_b32_e32 v8, 16, v220
	v_fmac_f32_e32 v20, v8, v8
	v_and_b32_e32 v8, 0xffff0000, v220
	v_fmac_f32_e32 v20, v8, v8
	v_lshlrev_b32_e32 v8, 16, v221
	v_fmac_f32_e32 v20, v8, v8
	v_and_b32_e32 v8, 0xffff0000, v221
	v_fmac_f32_e32 v20, v8, v8
	v_lshlrev_b32_e32 v8, 16, v222
	v_fmac_f32_e32 v20, v8, v8
	v_and_b32_e32 v8, 0xffff0000, v222
	v_fmac_f32_e32 v20, v8, v8
	v_lshlrev_b32_e32 v8, 16, v223
	v_fmac_f32_e32 v20, v8, v8
	v_and_b32_e32 v8, 0xffff0000, v223
	v_fmac_f32_e32 v20, v8, v8
	s_waitcnt vmcnt(4)
	v_lshlrev_b32_e32 v8, 16, v224
	v_and_b32_e32 v21, 0xffff0000, v224
	v_mul_f32_e32 v21, v21, v21
	v_fmac_f32_e32 v21, v8, v8
	v_lshlrev_b32_e32 v8, 16, v225
	v_fmac_f32_e32 v21, v8, v8
	v_and_b32_e32 v8, 0xffff0000, v225
	v_fmac_f32_e32 v21, v8, v8
	v_lshlrev_b32_e32 v8, 16, v226
	v_fmac_f32_e32 v21, v8, v8
	v_and_b32_e32 v8, 0xffff0000, v226
	v_fmac_f32_e32 v21, v8, v8
	v_lshlrev_b32_e32 v8, 16, v227
	v_fmac_f32_e32 v21, v8, v8
	v_and_b32_e32 v8, 0xffff0000, v227
	v_fmac_f32_e32 v21, v8, v8
	v_lshlrev_b32_e32 v8, 16, v228
	v_fmac_f32_e32 v21, v8, v8
	v_and_b32_e32 v8, 0xffff0000, v228
	v_fmac_f32_e32 v21, v8, v8
	v_lshlrev_b32_e32 v8, 16, v229
	v_fmac_f32_e32 v21, v8, v8
	v_and_b32_e32 v8, 0xffff0000, v229
	v_fmac_f32_e32 v21, v8, v8
	v_lshlrev_b32_e32 v8, 16, v230
	v_fmac_f32_e32 v21, v8, v8
	v_and_b32_e32 v8, 0xffff0000, v230
	v_fmac_f32_e32 v21, v8, v8
	v_lshlrev_b32_e32 v8, 16, v231
	v_fmac_f32_e32 v21, v8, v8
	v_and_b32_e32 v8, 0xffff0000, v231
	v_fmac_f32_e32 v21, v8, v8
	s_waitcnt vmcnt(2)
	v_lshlrev_b32_e32 v8, 16, v232
	v_and_b32_e32 v22, 0xffff0000, v232
	v_mul_f32_e32 v22, v22, v22
	v_fmac_f32_e32 v22, v8, v8
	v_lshlrev_b32_e32 v8, 16, v233
	v_fmac_f32_e32 v22, v8, v8
	v_and_b32_e32 v8, 0xffff0000, v233
	v_fmac_f32_e32 v22, v8, v8
	v_lshlrev_b32_e32 v8, 16, v234
	v_fmac_f32_e32 v22, v8, v8
	v_and_b32_e32 v8, 0xffff0000, v234
	v_fmac_f32_e32 v22, v8, v8
	v_lshlrev_b32_e32 v8, 16, v235
	v_fmac_f32_e32 v22, v8, v8
	v_and_b32_e32 v8, 0xffff0000, v235
	v_fmac_f32_e32 v22, v8, v8
	v_lshlrev_b32_e32 v8, 16, v236
	v_fmac_f32_e32 v22, v8, v8
	v_and_b32_e32 v8, 0xffff0000, v236
	v_fmac_f32_e32 v22, v8, v8
	v_lshlrev_b32_e32 v8, 16, v237
	v_fmac_f32_e32 v22, v8, v8
	v_and_b32_e32 v8, 0xffff0000, v237
	v_fmac_f32_e32 v22, v8, v8
	v_lshlrev_b32_e32 v8, 16, v238
	v_fmac_f32_e32 v22, v8, v8
	v_and_b32_e32 v8, 0xffff0000, v238
	v_fmac_f32_e32 v22, v8, v8
	v_lshlrev_b32_e32 v8, 16, v239
	v_fmac_f32_e32 v22, v8, v8
	v_and_b32_e32 v8, 0xffff0000, v239
	v_fmac_f32_e32 v22, v8, v8
	s_waitcnt vmcnt(0)
	v_lshlrev_b32_e32 v8, 16, v246
	v_and_b32_e32 v23, 0xffff0000, v246
	v_mul_f32_e32 v23, v23, v23
	v_fmac_f32_e32 v23, v8, v8
	v_lshlrev_b32_e32 v8, 16, v247
	v_fmac_f32_e32 v23, v8, v8
	v_and_b32_e32 v8, 0xffff0000, v247
	v_fmac_f32_e32 v23, v8, v8
	v_lshlrev_b32_e32 v8, 16, v248
	v_fmac_f32_e32 v23, v8, v8
	v_and_b32_e32 v8, 0xffff0000, v248
	v_fmac_f32_e32 v23, v8, v8
	v_lshlrev_b32_e32 v8, 16, v249
	v_fmac_f32_e32 v23, v8, v8
	v_and_b32_e32 v8, 0xffff0000, v249
	v_fmac_f32_e32 v23, v8, v8
	v_lshlrev_b32_e32 v8, 16, v250
	v_fmac_f32_e32 v23, v8, v8
	v_and_b32_e32 v8, 0xffff0000, v250
	v_fmac_f32_e32 v23, v8, v8
	v_lshlrev_b32_e32 v8, 16, v251
	v_fmac_f32_e32 v23, v8, v8
	v_and_b32_e32 v8, 0xffff0000, v251
	v_fmac_f32_e32 v23, v8, v8
	v_lshlrev_b32_e32 v8, 16, v252
	v_fmac_f32_e32 v23, v8, v8
	v_and_b32_e32 v8, 0xffff0000, v252
	v_fmac_f32_e32 v23, v8, v8
	v_lshlrev_b32_e32 v8, 16, v253
	v_fmac_f32_e32 v23, v8, v8
	v_and_b32_e32 v8, 0xffff0000, v253
	v_fmac_f32_e32 v23, v8, v8
	global_load_dwordx4 v[184:187], v[12:13], off
	global_load_dwordx4 v[188:191], v[12:13], off offset:1024
	v_lshl_add_u64 v[12:13], v[12:13], 0, s[80:81]
	global_load_dwordx4 v[192:195], v[12:13], off
	global_load_dwordx4 v[196:199], v[12:13], off offset:1024
	v_lshl_add_u64 v[12:13], v[12:13], 0, s[80:81]
	global_load_dwordx4 v[200:203], v[12:13], off
	global_load_dwordx4 v[204:207], v[12:13], off offset:1024
	v_lshl_add_u64 v[12:13], v[12:13], 0, s[80:81]
	global_load_dwordx4 v[208:211], v[12:13], off
	global_load_dwordx4 v[212:215], v[12:13], off offset:1024
	v_lshl_add_u64 v[12:13], v[12:13], 0, s[80:81]
	global_load_dwordx4 v[216:219], v[12:13], off
	global_load_dwordx4 v[220:223], v[12:13], off offset:1024
	v_lshl_add_u64 v[12:13], v[12:13], 0, s[80:81]
	global_load_dwordx4 v[224:227], v[12:13], off
	global_load_dwordx4 v[228:231], v[12:13], off offset:1024
	v_lshl_add_u64 v[12:13], v[12:13], 0, s[80:81]
	global_load_dwordx4 v[232:235], v[12:13], off
	global_load_dwordx4 v[236:239], v[12:13], off offset:1024
	v_lshl_add_u64 v[12:13], v[12:13], 0, s[80:81]
	global_load_dwordx4 v[246:249], v[12:13], off
	global_load_dwordx4 v[250:253], v[12:13], off offset:1024
	v_lshl_add_u64 v[12:13], v[12:13], 0, s[80:81]
	ds_bpermute_b32 v24, v0, v16
	ds_bpermute_b32 v25, v0, v17
	ds_bpermute_b32 v26, v0, v18
	ds_bpermute_b32 v27, v0, v19
	ds_bpermute_b32 v28, v0, v20
	ds_bpermute_b32 v29, v0, v21
	ds_bpermute_b32 v30, v0, v22
	ds_bpermute_b32 v31, v0, v23
	s_waitcnt lgkmcnt(0)
; __device__ __forceinline__ float bfel(const u32x4& v, int c) { const unsigned w = (c >> 1) == 0 ? v.x : (c >> 1) == 1 ? v.y : (c >> 1) == 2 ? v.z : v.w; return (c & 1) ? bfhi(w) : bflo(w); }
; __device__ __forceinline__ void gmlp_unit(const Params& p, LAS unsigned char* lds, int unit) {
;     ...
;     for (int q = wid; q < 128; q += 8) {
;         float ss = 0.f;
; #pragma unroll
;         for (int i = 0; i < 2; ++i) { const u32x4 v = *(const u32x4*)(GV + (size_t)(r0 + q) * 1024 + i * 512 + lane * 8);
; #pragma unroll
;             for (int c = 0; c < 8; ++c) { const float f = bfel(v, c); ss += f * f; } }
;         ss = wave_sum(ss);
;         if (lane == 0) rstd[q] = rsqrtf(ss * (1.f / 1024.f) + 1e-6f);
;     }
	v_add_f32_e32 v16, v16, v24
	v_add_f32_e32 v17, v17, v25
	v_add_f32_e32 v18, v18, v26
	v_add_f32_e32 v19, v19, v27
	v_add_f32_e32 v20, v20, v28
	v_add_f32_e32 v21, v21, v29
	v_add_f32_e32 v22, v22, v30
	v_add_f32_e32 v23, v23, v31
	ds_bpermute_b32 v24, v1, v16
	ds_bpermute_b32 v25, v1, v17
	ds_bpermute_b32 v26, v1, v18
	ds_bpermute_b32 v27, v1, v19
	ds_bpermute_b32 v28, v1, v20
	ds_bpermute_b32 v29, v1, v21
	ds_bpermute_b32 v30, v1, v22
	ds_bpermute_b32 v31, v1, v23
	s_waitcnt lgkmcnt(0)
	v_add_f32_e32 v16, v16, v24
	v_add_f32_e32 v17, v17, v25
	v_add_f32_e32 v18, v18, v26
	v_add_f32_e32 v19, v19, v27
	v_add_f32_e32 v20, v20, v28
	v_add_f32_e32 v21, v21, v29
	v_add_f32_e32 v22, v22, v30
	v_add_f32_e32 v23, v23, v31
	ds_bpermute_b32 v24, v2, v16
	ds_bpermute_b32 v25, v2, v17
	ds_bpermute_b32 v26, v2, v18
	ds_bpermute_b32 v27, v2, v19
	ds_bpermute_b32 v28, v2, v20
	ds_bpermute_b32 v29, v2, v21
	ds_bpermute_b32 v30, v2, v22
	ds_bpermute_b32 v31, v2, v23
	s_waitcnt lgkmcnt(0)
	v_add_f32_e32 v16, v16, v24
	v_add_f32_e32 v17, v17, v25
	v_add_f32_e32 v18, v18, v26
	v_add_f32_e32 v19, v19, v27
	v_add_f32_e32 v20, v20, v28
	v_add_f32_e32 v21, v21, v29
	v_add_f32_e32 v22, v22, v30
	v_add_f32_e32 v23, v23, v31
	ds_bpermute_b32 v24, v3, v16
	ds_bpermute_b32 v25, v3, v17
	ds_bpermute_b32 v26, v3, v18
	ds_bpermute_b32 v27, v3, v19
	ds_bpermute_b32 v28, v3, v20
	ds_bpermute_b32 v29, v3, v21
	ds_bpermute_b32 v30, v3, v22
	ds_bpermute_b32 v31, v3, v23
	s_waitcnt lgkmcnt(0)
	v_add_f32_e32 v16, v16, v24
	v_add_f32_e32 v17, v17, v25
	v_add_f32_e32 v18, v18, v26
	v_add_f32_e32 v19, v19, v27
	v_add_f32_e32 v20, v20, v28
	v_add_f32_e32 v21, v21, v29
	v_add_f32_e32 v22, v22, v30
	v_add_f32_e32 v23, v23, v31
	ds_bpermute_b32 v24, v4, v16
	ds_bpermute_b32 v25, v4, v17
	ds_bpermute_b32 v26, v4, v18
	ds_bpermute_b32 v27, v4, v19
	ds_bpermute_b32 v28, v4, v20
	ds_bpermute_b32 v29, v4, v21
	ds_bpermute_b32 v30, v4, v22
	ds_bpermute_b32 v31, v4, v23
	s_waitcnt lgkmcnt(0)
	v_add_f32_e32 v16, v16, v24
	v_add_f32_e32 v17, v17, v25
	v_add_f32_e32 v18, v18, v26
	v_add_f32_e32 v19, v19, v27
	v_add_f32_e32 v20, v20, v28
	v_add_f32_e32 v21, v21, v29
	v_add_f32_e32 v22, v22, v30
	v_add_f32_e32 v23, v23, v31
	ds_bpermute_b32 v24, v5, v16
	ds_bpermute_b32 v25, v5, v17
	ds_bpermute_b32 v26, v5, v18
	ds_bpermute_b32 v27, v5, v19
	ds_bpermute_b32 v28, v5, v20
	ds_bpermute_b32 v29, v5, v21
	ds_bpermute_b32 v30, v5, v22
	ds_bpermute_b32 v31, v5, v23
	s_waitcnt lgkmcnt(0)
	v_add_f32_e32 v16, v16, v24
	v_add_f32_e32 v17, v17, v25
	v_add_f32_e32 v18, v18, v26
	v_add_f32_e32 v19, v19, v27
	v_add_f32_e32 v20, v20, v28
	v_add_f32_e32 v21, v21, v29
	v_add_f32_e32 v22, v22, v30
	v_add_f32_e32 v23, v23, v31
	s_and_saveexec_b64 s[6:7], s[0:1]
	v_fmamk_f32 v16, v16, 0x3a800000, v147
	v_mul_f32_e32 v24, 0x4b800000, v16
	v_cmp_gt_f32_e32 vcc, s23, v16
	s_nop 1
	v_cndmask_b32_e32 v16, v16, v24, vcc
	v_rsq_f32_e32 v16, v16
	s_nop 0
	v_mul_f32_e32 v24, 0x45800000, v16
	v_cndmask_b32_e32 v16, v16, v24, vcc
	ds_write_b32 v146, v16 offset:0
	v_fmamk_f32 v17, v17, 0x3a800000, v147
	v_mul_f32_e32 v25, 0x4b800000, v17
	v_cmp_gt_f32_e32 vcc, s23, v17
	s_nop 1
	v_cndmask_b32_e32 v17, v17, v25, vcc
	v_rsq_f32_e32 v17, v17
	s_nop 0
	v_mul_f32_e32 v25, 0x45800000, v17
	v_cndmask_b32_e32 v17, v17, v25, vcc
	ds_write_b32 v146, v17 offset:32
	v_fmamk_f32 v18, v18, 0x3a800000, v147
	v_mul_f32_e32 v26, 0x4b800000, v18
	v_cmp_gt_f32_e32 vcc, s23, v18
	s_nop 1
	v_cndmask_b32_e32 v18, v18, v26, vcc
	v_rsq_f32_e32 v18, v18
	s_nop 0
	v_mul_f32_e32 v26, 0x45800000, v18
	v_cndmask_b32_e32 v18, v18, v26, vcc
	ds_write_b32 v146, v18 offset:64
	v_fmamk_f32 v19, v19, 0x3a800000, v147
	v_mul_f32_e32 v27, 0x4b800000, v19
	v_cmp_gt_f32_e32 vcc, s23, v19
	s_nop 1
	v_cndmask_b32_e32 v19, v19, v27, vcc
	v_rsq_f32_e32 v19, v19
	s_nop 0
	v_mul_f32_e32 v27, 0x45800000, v19
	v_cndmask_b32_e32 v19, v19, v27, vcc
	ds_write_b32 v146, v19 offset:96
	v_fmamk_f32 v20, v20, 0x3a800000, v147
	v_mul_f32_e32 v28, 0x4b800000, v20
	v_cmp_gt_f32_e32 vcc, s23, v20
	s_nop 1
	v_cndmask_b32_e32 v20, v20, v28, vcc
	v_rsq_f32_e32 v20, v20
	s_nop 0
	v_mul_f32_e32 v28, 0x45800000, v20
	v_cndmask_b32_e32 v20, v20, v28, vcc
	ds_write_b32 v146, v20 offset:128
	v_fmamk_f32 v21, v21, 0x3a800000, v147
	v_mul_f32_e32 v29, 0x4b800000, v21
	v_cmp_gt_f32_e32 vcc, s23, v21
	s_nop 1
	v_cndmask_b32_e32 v21, v21, v29, vcc
	v_rsq_f32_e32 v21, v21
	s_nop 0
	v_mul_f32_e32 v29, 0x45800000, v21
	v_cndmask_b32_e32 v21, v21, v29, vcc
	ds_write_b32 v146, v21 offset:160
	v_fmamk_f32 v22, v22, 0x3a800000, v147
	v_mul_f32_e32 v30, 0x4b800000, v22
	v_cmp_gt_f32_e32 vcc, s23, v22
	s_nop 1
	v_cndmask_b32_e32 v22, v22, v30, vcc
	v_rsq_f32_e32 v22, v22
	s_nop 0
	v_mul_f32_e32 v30, 0x45800000, v22
	v_cndmask_b32_e32 v22, v22, v30, vcc
	ds_write_b32 v146, v22 offset:192
	v_fmamk_f32 v23, v23, 0x3a800000, v147
	v_mul_f32_e32 v31, 0x4b800000, v23
	v_cmp_gt_f32_e32 vcc, s23, v23
	s_nop 1
	v_cndmask_b32_e32 v23, v23, v31, vcc
	v_rsq_f32_e32 v23, v23
	s_nop 0
	v_mul_f32_e32 v31, 0x45800000, v23
	v_cndmask_b32_e32 v23, v23, v31, vcc
	ds_write_b32 v146, v23 offset:224
	s_or_b64 exec, exec, s[6:7]
	s_waitcnt vmcnt(14)
; __device__ __forceinline__ float bfel(const u32x4& v, int c) { const unsigned w = (c >> 1) == 0 ? v.x : (c >> 1) == 1 ? v.y : (c >> 1) == 2 ? v.z : v.w; return (c & 1) ? bfhi(w) : bflo(w); }
; __device__ __forceinline__ void gmlp_unit(const Params& p, LAS unsigned char* lds, int unit) {
;     ...
;     for (int q = wid; q < 128; q += 8) {
;         float ss = 0.f;
; #pragma unroll
;         for (int i = 0; i < 2; ++i) { const u32x4 v = *(const u32x4*)(GV + (size_t)(r0 + q) * 1024 + i * 512 + lane * 8);
; #pragma unroll
;             for (int c = 0; c < 8; ++c) { const float f = bfel(v, c); ss += f * f; } }
;         ss = wave_sum(ss);
;         if (lane == 0) rstd[q] = rsqrtf(ss * (1.f / 1024.f) + 1e-6f);
;     }
	v_lshlrev_b32_e32 v8, 16, v184
	v_and_b32_e32 v16, 0xffff0000, v184
	v_mul_f32_e32 v16, v16, v16
	v_fmac_f32_e32 v16, v8, v8
	v_lshlrev_b32_e32 v8, 16, v185
	v_fmac_f32_e32 v16, v8, v8
	v_and_b32_e32 v8, 0xffff0000, v185
	v_fmac_f32_e32 v16, v8, v8
	v_lshlrev_b32_e32 v8, 16, v186
	v_fmac_f32_e32 v16, v8, v8
	v_and_b32_e32 v8, 0xffff0000, v186
	v_fmac_f32_e32 v16, v8, v8
	v_lshlrev_b32_e32 v8, 16, v187
	v_fmac_f32_e32 v16, v8, v8
	v_and_b32_e32 v8, 0xffff0000, v187
	v_fmac_f32_e32 v16, v8, v8
	v_lshlrev_b32_e32 v8, 16, v188
	v_fmac_f32_e32 v16, v8, v8
	v_and_b32_e32 v8, 0xffff0000, v188
	v_fmac_f32_e32 v16, v8, v8
	v_lshlrev_b32_e32 v8, 16, v189
	v_fmac_f32_e32 v16, v8, v8
	v_and_b32_e32 v8, 0xffff0000, v189
	v_fmac_f32_e32 v16, v8, v8
	v_lshlrev_b32_e32 v8, 16, v190
	v_fmac_f32_e32 v16, v8, v8
	v_and_b32_e32 v8, 0xffff0000, v190
	v_fmac_f32_e32 v16, v8, v8
	v_lshlrev_b32_e32 v8, 16, v191
	v_fmac_f32_e32 v16, v8, v8
	v_and_b32_e32 v8, 0xffff0000, v191
	v_fmac_f32_e32 v16, v8, v8
	s_waitcnt vmcnt(12)
	v_lshlrev_b32_e32 v8, 16, v192
	v_and_b32_e32 v17, 0xffff0000, v192
	v_mul_f32_e32 v17, v17, v17
	v_fmac_f32_e32 v17, v8, v8
	v_lshlrev_b32_e32 v8, 16, v193
	v_fmac_f32_e32 v17, v8, v8
	v_and_b32_e32 v8, 0xffff0000, v193
	v_fmac_f32_e32 v17, v8, v8
	v_lshlrev_b32_e32 v8, 16, v194
	v_fmac_f32_e32 v17, v8, v8
	v_and_b32_e32 v8, 0xffff0000, v194
	v_fmac_f32_e32 v17, v8, v8
	v_lshlrev_b32_e32 v8, 16, v195
	v_fmac_f32_e32 v17, v8, v8
	v_and_b32_e32 v8, 0xffff0000, v195
	v_fmac_f32_e32 v17, v8, v8
	v_lshlrev_b32_e32 v8, 16, v196
	v_fmac_f32_e32 v17, v8, v8
	v_and_b32_e32 v8, 0xffff0000, v196
	v_fmac_f32_e32 v17, v8, v8
	v_lshlrev_b32_e32 v8, 16, v197
	v_fmac_f32_e32 v17, v8, v8
	v_and_b32_e32 v8, 0xffff0000, v197
	v_fmac_f32_e32 v17, v8, v8
	v_lshlrev_b32_e32 v8, 16, v198
	v_fmac_f32_e32 v17, v8, v8
	v_and_b32_e32 v8, 0xffff0000, v198
	v_fmac_f32_e32 v17, v8, v8
	v_lshlrev_b32_e32 v8, 16, v199
	v_fmac_f32_e32 v17, v8, v8
	v_and_b32_e32 v8, 0xffff0000, v199
	v_fmac_f32_e32 v17, v8, v8
	s_waitcnt vmcnt(10)
	v_lshlrev_b32_e32 v8, 16, v200
	v_and_b32_e32 v18, 0xffff0000, v200
	v_mul_f32_e32 v18, v18, v18
	v_fmac_f32_e32 v18, v8, v8
	v_lshlrev_b32_e32 v8, 16, v201
	v_fmac_f32_e32 v18, v8, v8
	v_and_b32_e32 v8, 0xffff0000, v201
	v_fmac_f32_e32 v18, v8, v8
	v_lshlrev_b32_e32 v8, 16, v202
	v_fmac_f32_e32 v18, v8, v8
	v_and_b32_e32 v8, 0xffff0000, v202
	v_fmac_f32_e32 v18, v8, v8
	v_lshlrev_b32_e32 v8, 16, v203
	v_fmac_f32_e32 v18, v8, v8
	v_and_b32_e32 v8, 0xffff0000, v203
	v_fmac_f32_e32 v18, v8, v8
	v_lshlrev_b32_e32 v8, 16, v204
	v_fmac_f32_e32 v18, v8, v8
	v_and_b32_e32 v8, 0xffff0000, v204
	v_fmac_f32_e32 v18, v8, v8
	v_lshlrev_b32_e32 v8, 16, v205
	v_fmac_f32_e32 v18, v8, v8
	v_and_b32_e32 v8, 0xffff0000, v205
	v_fmac_f32_e32 v18, v8, v8
	v_lshlrev_b32_e32 v8, 16, v206
	v_fmac_f32_e32 v18, v8, v8
	v_and_b32_e32 v8, 0xffff0000, v206
	v_fmac_f32_e32 v18, v8, v8
	v_lshlrev_b32_e32 v8, 16, v207
	v_fmac_f32_e32 v18, v8, v8
	v_and_b32_e32 v8, 0xffff0000, v207
	v_fmac_f32_e32 v18, v8, v8
	s_waitcnt vmcnt(8)
	v_lshlrev_b32_e32 v8, 16, v208
	v_and_b32_e32 v19, 0xffff0000, v208
	v_mul_f32_e32 v19, v19, v19
	v_fmac_f32_e32 v19, v8, v8
	v_lshlrev_b32_e32 v8, 16, v209
	v_fmac_f32_e32 v19, v8, v8
	v_and_b32_e32 v8, 0xffff0000, v209
	v_fmac_f32_e32 v19, v8, v8
	v_lshlrev_b32_e32 v8, 16, v210
	v_fmac_f32_e32 v19, v8, v8
	v_and_b32_e32 v8, 0xffff0000, v210
	v_fmac_f32_e32 v19, v8, v8
	v_lshlrev_b32_e32 v8, 16, v211
	v_fmac_f32_e32 v19, v8, v8
	v_and_b32_e32 v8, 0xffff0000, v211
	v_fmac_f32_e32 v19, v8, v8
	v_lshlrev_b32_e32 v8, 16, v212
	v_fmac_f32_e32 v19, v8, v8
	v_and_b32_e32 v8, 0xffff0000, v212
	v_fmac_f32_e32 v19, v8, v8
	v_lshlrev_b32_e32 v8, 16, v213
	v_fmac_f32_e32 v19, v8, v8
	v_and_b32_e32 v8, 0xffff0000, v213
	v_fmac_f32_e32 v19, v8, v8
	v_lshlrev_b32_e32 v8, 16, v214
	v_fmac_f32_e32 v19, v8, v8
	v_and_b32_e32 v8, 0xffff0000, v214
	v_fmac_f32_e32 v19, v8, v8
	v_lshlrev_b32_e32 v8, 16, v215
	v_fmac_f32_e32 v19, v8, v8
	v_and_b32_e32 v8, 0xffff0000, v215
	v_fmac_f32_e32 v19, v8, v8
	s_waitcnt vmcnt(6)
	v_lshlrev_b32_e32 v8, 16, v216
	v_and_b32_e32 v20, 0xffff0000, v216
	v_mul_f32_e32 v20, v20, v20
	v_fmac_f32_e32 v20, v8, v8
	v_lshlrev_b32_e32 v8, 16, v217
	v_fmac_f32_e32 v20, v8, v8
	v_and_b32_e32 v8, 0xffff0000, v217
	v_fmac_f32_e32 v20, v8, v8
	v_lshlrev_b32_e32 v8, 16, v218
	v_fmac_f32_e32 v20, v8, v8
	v_and_b32_e32 v8, 0xffff0000, v218
	v_fmac_f32_e32 v20, v8, v8
	v_lshlrev_b32_e32 v8, 16, v219
	v_fmac_f32_e32 v20, v8, v8
	v_and_b32_e32 v8, 0xffff0000, v219
	v_fmac_f32_e32 v20, v8, v8
	v_lshlrev_b32_e32 v8, 16, v220
	v_fmac_f32_e32 v20, v8, v8
	v_and_b32_e32 v8, 0xffff0000, v220
	v_fmac_f32_e32 v20, v8, v8
	v_lshlrev_b32_e32 v8, 16, v221
	v_fmac_f32_e32 v20, v8, v8
	v_and_b32_e32 v8, 0xffff0000, v221
	v_fmac_f32_e32 v20, v8, v8
	v_lshlrev_b32_e32 v8, 16, v222
	v_fmac_f32_e32 v20, v8, v8
	v_and_b32_e32 v8, 0xffff0000, v222
	v_fmac_f32_e32 v20, v8, v8
	v_lshlrev_b32_e32 v8, 16, v223
	v_fmac_f32_e32 v20, v8, v8
	v_and_b32_e32 v8, 0xffff0000, v223
	v_fmac_f32_e32 v20, v8, v8
	s_waitcnt vmcnt(4)
	v_lshlrev_b32_e32 v8, 16, v224
	v_and_b32_e32 v21, 0xffff0000, v224
	v_mul_f32_e32 v21, v21, v21
	v_fmac_f32_e32 v21, v8, v8
	v_lshlrev_b32_e32 v8, 16, v225
	v_fmac_f32_e32 v21, v8, v8
	v_and_b32_e32 v8, 0xffff0000, v225
	v_fmac_f32_e32 v21, v8, v8
	v_lshlrev_b32_e32 v8, 16, v226
	v_fmac_f32_e32 v21, v8, v8
	v_and_b32_e32 v8, 0xffff0000, v226
	v_fmac_f32_e32 v21, v8, v8
	v_lshlrev_b32_e32 v8, 16, v227
	v_fmac_f32_e32 v21, v8, v8
	v_and_b32_e32 v8, 0xffff0000, v227
	v_fmac_f32_e32 v21, v8, v8
	v_lshlrev_b32_e32 v8, 16, v228
	v_fmac_f32_e32 v21, v8, v8
	v_and_b32_e32 v8, 0xffff0000, v228
	v_fmac_f32_e32 v21, v8, v8
	v_lshlrev_b32_e32 v8, 16, v229
	v_fmac_f32_e32 v21, v8, v8
	v_and_b32_e32 v8, 0xffff0000, v229
	v_fmac_f32_e32 v21, v8, v8
	v_lshlrev_b32_e32 v8, 16, v230
	v_fmac_f32_e32 v21, v8, v8
	v_and_b32_e32 v8, 0xffff0000, v230
	v_fmac_f32_e32 v21, v8, v8
	v_lshlrev_b32_e32 v8, 16, v231
	v_fmac_f32_e32 v21, v8, v8
	v_and_b32_e32 v8, 0xffff0000, v231
	v_fmac_f32_e32 v21, v8, v8
	s_waitcnt vmcnt(2)
; __device__ __forceinline__ float bfel(const u32x4& v, int c) { const unsigned w = (c >> 1) == 0 ? v.x : (c >> 1) == 1 ? v.y : (c >> 1) == 2 ? v.z : v.w; return (c & 1) ? bfhi(w) : bflo(w); }
; __device__ __forceinline__ void gmlp_unit(const Params& p, LAS unsigned char* lds, int unit) {
;     ...
;     for (int q = wid; q < 128; q += 8) {
;         float ss = 0.f;
; #pragma unroll
;         for (int i = 0; i < 2; ++i) { const u32x4 v = *(const u32x4*)(GV + (size_t)(r0 + q) * 1024 + i * 512 + lane * 8);
; #pragma unroll
;             for (int c = 0; c < 8; ++c) { const float f = bfel(v, c); ss += f * f; } }
;         ss = wave_sum(ss);
;         if (lane == 0) rstd[q] = rsqrtf(ss * (1.f / 1024.f) + 1e-6f);
;     }
	v_lshlrev_b32_e32 v8, 16, v232
	v_and_b32_e32 v22, 0xffff0000, v232
	v_mul_f32_e32 v22, v22, v22
	v_fmac_f32_e32 v22, v8, v8
	v_lshlrev_b32_e32 v8, 16, v233
	v_fmac_f32_e32 v22, v8, v8
	v_and_b32_e32 v8, 0xffff0000, v233
	v_fmac_f32_e32 v22, v8, v8
	v_lshlrev_b32_e32 v8, 16, v234
	v_fmac_f32_e32 v22, v8, v8
	v_and_b32_e32 v8, 0xffff0000, v234
	v_fmac_f32_e32 v22, v8, v8
	v_lshlrev_b32_e32 v8, 16, v235
	v_fmac_f32_e32 v22, v8, v8
	v_and_b32_e32 v8, 0xffff0000, v235
	v_fmac_f32_e32 v22, v8, v8
	v_lshlrev_b32_e32 v8, 16, v236
	v_fmac_f32_e32 v22, v8, v8
	v_and_b32_e32 v8, 0xffff0000, v236
	v_fmac_f32_e32 v22, v8, v8
	v_lshlrev_b32_e32 v8, 16, v237
	v_fmac_f32_e32 v22, v8, v8
	v_and_b32_e32 v8, 0xffff0000, v237
	v_fmac_f32_e32 v22, v8, v8
	v_lshlrev_b32_e32 v8, 16, v238
	v_fmac_f32_e32 v22, v8, v8
	v_and_b32_e32 v8, 0xffff0000, v238
	v_fmac_f32_e32 v22, v8, v8
	v_lshlrev_b32_e32 v8, 16, v239
	v_fmac_f32_e32 v22, v8, v8
	v_and_b32_e32 v8, 0xffff0000, v239
	v_fmac_f32_e32 v22, v8, v8
	s_waitcnt vmcnt(0)
	v_lshlrev_b32_e32 v8, 16, v246
	v_and_b32_e32 v23, 0xffff0000, v246
	v_mul_f32_e32 v23, v23, v23
	v_fmac_f32_e32 v23, v8, v8
	v_lshlrev_b32_e32 v8, 16, v247
	v_fmac_f32_e32 v23, v8, v8
	v_and_b32_e32 v8, 0xffff0000, v247
	v_fmac_f32_e32 v23, v8, v8
	v_lshlrev_b32_e32 v8, 16, v248
	v_fmac_f32_e32 v23, v8, v8
	v_and_b32_e32 v8, 0xffff0000, v248
	v_fmac_f32_e32 v23, v8, v8
	v_lshlrev_b32_e32 v8, 16, v249
	v_fmac_f32_e32 v23, v8, v8
	v_and_b32_e32 v8, 0xffff0000, v249
	v_fmac_f32_e32 v23, v8, v8
	v_lshlrev_b32_e32 v8, 16, v250
	v_fmac_f32_e32 v23, v8, v8
	v_and_b32_e32 v8, 0xffff0000, v250
	v_fmac_f32_e32 v23, v8, v8
	v_lshlrev_b32_e32 v8, 16, v251
	v_fmac_f32_e32 v23, v8, v8
	v_and_b32_e32 v8, 0xffff0000, v251
	v_fmac_f32_e32 v23, v8, v8
	v_lshlrev_b32_e32 v8, 16, v252
	v_fmac_f32_e32 v23, v8, v8
	v_and_b32_e32 v8, 0xffff0000, v252
	v_fmac_f32_e32 v23, v8, v8
	v_lshlrev_b32_e32 v8, 16, v253
	v_fmac_f32_e32 v23, v8, v8
	v_and_b32_e32 v8, 0xffff0000, v253
	v_fmac_f32_e32 v23, v8, v8
	ds_bpermute_b32 v24, v0, v16
	ds_bpermute_b32 v25, v0, v17
	ds_bpermute_b32 v26, v0, v18
	ds_bpermute_b32 v27, v0, v19
	ds_bpermute_b32 v28, v0, v20
	ds_bpermute_b32 v29, v0, v21
	ds_bpermute_b32 v30, v0, v22
	ds_bpermute_b32 v31, v0, v23
	s_waitcnt lgkmcnt(0)
	v_add_f32_e32 v16, v16, v24
	v_add_f32_e32 v17, v17, v25
	v_add_f32_e32 v18, v18, v26
	v_add_f32_e32 v19, v19, v27
	v_add_f32_e32 v20, v20, v28
	v_add_f32_e32 v21, v21, v29
	v_add_f32_e32 v22, v22, v30
	v_add_f32_e32 v23, v23, v31
	ds_bpermute_b32 v24, v1, v16
	ds_bpermute_b32 v25, v1, v17
	ds_bpermute_b32 v26, v1, v18
	ds_bpermute_b32 v27, v1, v19
	ds_bpermute_b32 v28, v1, v20
	ds_bpermute_b32 v29, v1, v21
	ds_bpermute_b32 v30, v1, v22
	ds_bpermute_b32 v31, v1, v23
	s_waitcnt lgkmcnt(0)
	v_add_f32_e32 v16, v16, v24
	v_add_f32_e32 v17, v17, v25
	v_add_f32_e32 v18, v18, v26
	v_add_f32_e32 v19, v19, v27
	v_add_f32_e32 v20, v20, v28
	v_add_f32_e32 v21, v21, v29
	v_add_f32_e32 v22, v22, v30
	v_add_f32_e32 v23, v23, v31
	ds_bpermute_b32 v24, v2, v16
	ds_bpermute_b32 v25, v2, v17
	ds_bpermute_b32 v26, v2, v18
	ds_bpermute_b32 v27, v2, v19
	ds_bpermute_b32 v28, v2, v20
	ds_bpermute_b32 v29, v2, v21
	ds_bpermute_b32 v30, v2, v22
	ds_bpermute_b32 v31, v2, v23
	s_waitcnt lgkmcnt(0)
	v_add_f32_e32 v16, v16, v24
	v_add_f32_e32 v17, v17, v25
	v_add_f32_e32 v18, v18, v26
	v_add_f32_e32 v19, v19, v27
	v_add_f32_e32 v20, v20, v28
	v_add_f32_e32 v21, v21, v29
	v_add_f32_e32 v22, v22, v30
	v_add_f32_e32 v23, v23, v31
	ds_bpermute_b32 v24, v3, v16
	ds_bpermute_b32 v25, v3, v17
	ds_bpermute_b32 v26, v3, v18
	ds_bpermute_b32 v27, v3, v19
	ds_bpermute_b32 v28, v3, v20
	ds_bpermute_b32 v29, v3, v21
	ds_bpermute_b32 v30, v3, v22
	ds_bpermute_b32 v31, v3, v23
	s_waitcnt lgkmcnt(0)
	v_add_f32_e32 v16, v16, v24
	v_add_f32_e32 v17, v17, v25
	v_add_f32_e32 v18, v18, v26
	v_add_f32_e32 v19, v19, v27
	v_add_f32_e32 v20, v20, v28
	v_add_f32_e32 v21, v21, v29
	v_add_f32_e32 v22, v22, v30
	v_add_f32_e32 v23, v23, v31
	ds_bpermute_b32 v24, v4, v16
	ds_bpermute_b32 v25, v4, v17
	ds_bpermute_b32 v26, v4, v18
	ds_bpermute_b32 v27, v4, v19
	ds_bpermute_b32 v28, v4, v20
	ds_bpermute_b32 v29, v4, v21
	ds_bpermute_b32 v30, v4, v22
	ds_bpermute_b32 v31, v4, v23
	s_waitcnt lgkmcnt(0)
	v_add_f32_e32 v16, v16, v24
	v_add_f32_e32 v17, v17, v25
	v_add_f32_e32 v18, v18, v26
	v_add_f32_e32 v19, v19, v27
	v_add_f32_e32 v20, v20, v28
	v_add_f32_e32 v21, v21, v29
	v_add_f32_e32 v22, v22, v30
	v_add_f32_e32 v23, v23, v31
	ds_bpermute_b32 v24, v5, v16
	ds_bpermute_b32 v25, v5, v17
	ds_bpermute_b32 v26, v5, v18
	ds_bpermute_b32 v27, v5, v19
	ds_bpermute_b32 v28, v5, v20
	ds_bpermute_b32 v29, v5, v21
	ds_bpermute_b32 v30, v5, v22
	ds_bpermute_b32 v31, v5, v23
	s_waitcnt lgkmcnt(0)
; #define LAS __attribute__((address_space(3)))
; __device__ __forceinline__ unsigned cvt_pk_bf16(float lo, float hi) { unsigned r; asm volatile("v_cvt_pk_bf16_f32 %0, %1, %2" : "=v"(r) : "v"(lo), "v"(hi)); return r; }
; __device__ __forceinline__ float bfel(const u32x4& v, int c) { const unsigned w = (c >> 1) == 0 ? v.x : (c >> 1) == 1 ? v.y : (c >> 1) == 2 ? v.z : v.w; return (c & 1) ? bfhi(w) : bflo(w); }
; __device__ __forceinline__ void gmlp_unit(const Params& p, LAS unsigned char* lds, int unit) {
;     ...
;     for (int q = wid; q < 128; q += 8) {
;         float ss = 0.f;
; #pragma unroll
;         for (int i = 0; i < 2; ++i) { const u32x4 v = *(const u32x4*)(GV + (size_t)(r0 + q) * 1024 + i * 512 + lane * 8);
; #pragma unroll
;             for (int c = 0; c < 8; ++c) { const float f = bfel(v, c); ss += f * f; } }
;         ss = wave_sum(ss);
;         if (lane == 0) rstd[q] = rsqrtf(ss * (1.f / 1024.f) + 1e-6f);
;     }
;     ...
;         for (int i = 0; i < 8; ++i) { const int idx = t + 512 * i, pr = idx >> 5, q4 = (idx & 31) * 4; const f32x4 v = *(const f32x4*)(ws_ + pr * 128 + q4);
;             u32x2 o; o.x = cvt_pk_bf16(v[0], v[1]); o.y = cvt_pk_bf16(v[2], v[3]); *(LAS u32x2*)(Wt + pr * 136 + q4) = o; }
;         const float* gn = p.in[16] + g * 128;
; #pragma unroll
;         for (int i = 0; i < 4; ++i) { const int d8 = (t & 15) * 8, q = (t >> 4) + 32 * i; const u32x4 v = *(const u32x4*)(GV + (size_t)(r0 + q) * 1024 + g * 128 + d8); const float rs = rstd[q];
; #pragma unroll
;             for (int c = 0; c < 8; ++c) { const float f = bfel(v, c) * rs * gn[d8 + c]; vnT[(d8 + c) * 136 + q] = (bf16_t)(cvt_pk_bf16(f, 0.f) & 0xffffu); } }
	v_add_f32_e32 v16, v16, v24
	v_add_f32_e32 v17, v17, v25
	v_add_f32_e32 v18, v18, v26
	v_add_f32_e32 v19, v19, v27
	v_add_f32_e32 v20, v20, v28
	v_add_f32_e32 v21, v21, v29
	v_add_f32_e32 v22, v22, v30
	v_add_f32_e32 v23, v23, v31
	s_and_saveexec_b64 s[6:7], s[0:1]
	v_fmamk_f32 v16, v16, 0x3a800000, v147
	v_mul_f32_e32 v24, 0x4b800000, v16
	v_cmp_gt_f32_e32 vcc, s23, v16
	s_nop 1
	v_cndmask_b32_e32 v16, v16, v24, vcc
	v_rsq_f32_e32 v16, v16
	s_nop 0
	v_mul_f32_e32 v24, 0x45800000, v16
	v_cndmask_b32_e32 v16, v16, v24, vcc
	ds_write_b32 v146, v16 offset:256
	v_fmamk_f32 v17, v17, 0x3a800000, v147
	v_mul_f32_e32 v25, 0x4b800000, v17
	v_cmp_gt_f32_e32 vcc, s23, v17
	s_nop 1
	v_cndmask_b32_e32 v17, v17, v25, vcc
	v_rsq_f32_e32 v17, v17
	s_nop 0
	v_mul_f32_e32 v25, 0x45800000, v17
	v_cndmask_b32_e32 v17, v17, v25, vcc
	ds_write_b32 v146, v17 offset:288
	v_fmamk_f32 v18, v18, 0x3a800000, v147
	v_mul_f32_e32 v26, 0x4b800000, v18
	v_cmp_gt_f32_e32 vcc, s23, v18
	s_nop 1
	v_cndmask_b32_e32 v18, v18, v26, vcc
	v_rsq_f32_e32 v18, v18
	s_nop 0
	v_mul_f32_e32 v26, 0x45800000, v18
	v_cndmask_b32_e32 v18, v18, v26, vcc
	ds_write_b32 v146, v18 offset:320
	v_fmamk_f32 v19, v19, 0x3a800000, v147
	v_mul_f32_e32 v27, 0x4b800000, v19
	v_cmp_gt_f32_e32 vcc, s23, v19
	s_nop 1
	v_cndmask_b32_e32 v19, v19, v27, vcc
	v_rsq_f32_e32 v19, v19
	s_nop 0
	v_mul_f32_e32 v27, 0x45800000, v19
	v_cndmask_b32_e32 v19, v19, v27, vcc
	ds_write_b32 v146, v19 offset:352
	v_fmamk_f32 v20, v20, 0x3a800000, v147
	v_mul_f32_e32 v28, 0x4b800000, v20
	v_cmp_gt_f32_e32 vcc, s23, v20
	s_nop 1
	v_cndmask_b32_e32 v20, v20, v28, vcc
	v_rsq_f32_e32 v20, v20
	s_nop 0
	v_mul_f32_e32 v28, 0x45800000, v20
	v_cndmask_b32_e32 v20, v20, v28, vcc
	ds_write_b32 v146, v20 offset:384
	v_fmamk_f32 v21, v21, 0x3a800000, v147
	v_mul_f32_e32 v29, 0x4b800000, v21
	v_cmp_gt_f32_e32 vcc, s23, v21
	s_nop 1
	v_cndmask_b32_e32 v21, v21, v29, vcc
	v_rsq_f32_e32 v21, v21
	s_nop 0
	v_mul_f32_e32 v29, 0x45800000, v21
	v_cndmask_b32_e32 v21, v21, v29, vcc
	ds_write_b32 v146, v21 offset:416
	v_fmamk_f32 v22, v22, 0x3a800000, v147
	v_mul_f32_e32 v30, 0x4b800000, v22
	v_cmp_gt_f32_e32 vcc, s23, v22
	s_nop 1
	v_cndmask_b32_e32 v22, v22, v30, vcc
	v_rsq_f32_e32 v22, v22
	s_nop 0
	v_mul_f32_e32 v30, 0x45800000, v22
	v_cndmask_b32_e32 v22, v22, v30, vcc
	ds_write_b32 v146, v22 offset:448
	v_fmamk_f32 v23, v23, 0x3a800000, v147
	v_mul_f32_e32 v31, 0x4b800000, v23
	v_cmp_gt_f32_e32 vcc, s23, v23
	s_nop 1
	v_cndmask_b32_e32 v23, v23, v31, vcc
	v_rsq_f32_e32 v23, v23
	s_nop 0
	v_mul_f32_e32 v31, 0x45800000, v23
	v_cndmask_b32_e32 v23, v23, v31, vcc
	ds_write_b32 v146, v23 offset:480
	s_or_b64 exec, exec, s[6:7]
	v_ashrrev_i32_e32 v113, 31, v112
	v_lshlrev_b64 v[0:1], 12, v[112:113]
	v_lshl_add_u64 v[16:17], v[110:111], 0, v[0:1]
	v_lshlrev_b64 v[0:1], 11, v[112:113]
	v_ashrrev_i32_e32 v121, 31, v120
	v_lshl_add_u64 v[18:19], v[110:111], 0, v[0:1]
	v_lshlrev_b64 v[0:1], 11, v[120:121]
	v_ashrrev_i32_e32 v123, 31, v122
	v_lshl_add_u64 v[20:21], v[118:119], 0, v[0:1]
	v_lshlrev_b64 v[0:1], 11, v[122:123]
	v_ashrrev_i32_e32 v125, 31, v124
	v_lshl_add_u64 v[22:23], v[118:119], 0, v[0:1]
	v_lshlrev_b64 v[0:1], 11, v[124:125]
	v_ashrrev_i32_e32 v127, 31, v126
	v_lshl_add_u64 v[24:25], v[118:119], 0, v[0:1]
	v_lshlrev_b64 v[0:1], 11, v[126:127]
	v_lshl_add_u64 v[26:27], v[118:119], 0, v[0:1]
	s_mov_b64 s[4:5], 0
	v_mov_b64_e32 v[28:29], v[134:135]
	v_mov_b64_e32 v[30:31], v[132:133]
	v_mov_b64_e32 v[32:33], v[130:131]
	v_mov_b64_e32 v[34:35], v[128:129]
	v_mov_b64_e32 v[36:37], v[116:117]
	s_mov_b64 s[6:7], 0
	v_and_b32_e32 v8, 31, v140
	v_lshrrev_b32_e32 v9, 5, v140
	v_readlane_b32 s82, v254, 18
	v_readlane_b32 s83, v254, 19
	v_lshl_add_u32 v10, v8, 2, s3
	v_lshlrev_b32_e32 v10, 11, v10
	v_lshl_add_u32 v10, v9, 4, v10
	v_mov_b32_e32 v11, 0
	v_lshl_add_u64 v[20:21], s[74:75], 0, v[10:11]
	s_mov_b64 s[80:81], 0x231a4000
	v_lshl_add_u64 v[20:21], v[20:21], 0, s[80:81]
	s_mov_b64 s[80:81], 0x1000
	v_lshl_add_u64 v[22:23], v[20:21], 0, s[80:81]
	v_lshlrev_b32_e32 v10, 5, v9
	v_lshl_add_u64 v[24:25], s[82:83], 0, v[10:11]
	v_mul_u32_u24_e32 v26, 0x880, v9
	v_lshl_add_u32 v26, v8, 3, v26
	v_lshlrev_b32_e32 v27, 4, v8
	v_add_u32_e32 v27, 0x11000, v27
	s_waitcnt lgkmcnt(0)
	s_barrier
; #define LAS __attribute__((address_space(3)))
; __device__ __forceinline__ unsigned cvt_pk_bf16(float lo, float hi) { unsigned r; asm volatile("v_cvt_pk_bf16_f32 %0, %1, %2" : "=v"(r) : "v"(lo), "v"(hi)); return r; }
; __device__ __forceinline__ float bfel(const u32x4& v, int c) { const unsigned w = (c >> 1) == 0 ? v.x : (c >> 1) == 1 ? v.y : (c >> 1) == 2 ? v.z : v.w; return (c & 1) ? bfhi(w) : bflo(w); }
; __device__ __forceinline__ void gmlp_unit(const Params& p, LAS unsigned char* lds, int unit) {
;     ...
;         const float* ws_ = p.in[17] + (size_t)g * 128 * 128;
; #pragma unroll
;         for (int i = 0; i < 8; ++i) { const int idx = t + 512 * i, pr = idx >> 5, q4 = (idx & 31) * 4; const f32x4 v = *(const f32x4*)(ws_ + pr * 128 + q4);
;             u32x2 o; o.x = cvt_pk_bf16(v[0], v[1]); o.y = cvt_pk_bf16(v[2], v[3]); *(LAS u32x2*)(Wt + pr * 136 + q4) = o; }
;         const float* gn = p.in[16] + g * 128;
; #pragma unroll
;         for (int i = 0; i < 4; ++i) { const int d8 = (t & 15) * 8, q = (t >> 4) + 32 * i; const u32x4 v = *(const u32x4*)(GV + (size_t)(r0 + q) * 1024 + g * 128 + d8); const float rs = rstd[q];
; #pragma unroll
;             for (int c = 0; c < 8; ++c) { const float f = bfel(v, c) * rs * gn[d8 + c]; vnT[(d8 + c) * 136 + q] = (bf16_t)(cvt_pk_bf16(f, 0.f) & 0xffffu); } }
.LBB0_1335:
	v_lshl_add_u64 v[2:3], v[34:35], 0, v[114:115]
	v_lshl_add_u64 v[8:9], v[32:33], 0, v[114:115]
	v_lshl_add_u64 v[10:11], v[30:31], 0, v[114:115]
	v_lshl_add_u64 v[12:13], v[28:29], 0, v[114:115]
	v_lshl_add_u64 v[14:15], v[36:37], 0, v[114:115]
	global_load_dwordx4 v[184:187], v[2:3], off
	global_load_dwordx4 v[188:191], v[8:9], off
	v_add_co_u32_e32 v46, vcc, s22, v2
	s_nop 1
	v_addc_co_u32_e32 v47, vcc, 0, v3, vcc
	v_add_co_u32_e32 v48, vcc, s40, v2
	s_nop 1
	v_addc_co_u32_e32 v49, vcc, 0, v3, vcc
	v_add_co_u32_e32 v50, vcc, s41, v2
	s_nop 1
	v_addc_co_u32_e32 v51, vcc, 0, v3, vcc
	global_load_dwordx4 v[192:195], v[46:47], off
	global_load_dwordx4 v[196:199], v[10:11], off
	global_load_dwordx4 v[200:203], v[48:49], off
	global_load_dwordx4 v[204:207], v[12:13], off
	global_load_dwordx4 v[208:211], v[50:51], off
	global_load_dwordx4 v[212:215], v[14:15], off
	v_lshl_add_u64 v[38:39], v[20:21], 0, s[6:7]
	v_lshl_add_u64 v[40:41], v[22:23], 0, s[6:7]
	v_lshl_add_u64 v[0:1], v[24:25], 0, s[4:5]
	global_load_dwordx4 v[216:219], v[38:39], off
	global_load_dwordx4 v[220:223], v[38:39], off offset:2048
	global_load_dwordx4 v[224:227], v[40:41], off
	global_load_dwordx4 v[228:231], v[40:41], off offset:2048
	global_load_dwordx4 v[232:235], v[0:1], off
	global_load_dwordx4 v[236:239], v[0:1], off offset:16
	v_lshl_add_u64 v[4:5], v[18:19], 0, s[6:7]
	v_add_co_u32_e32 v94, vcc, s42, v4
	s_nop 1
	v_addc_co_u32_e32 v95, vcc, 0, v5, vcc
	v_lshl_add_u64 v[4:5], v[108:109], 0, s[4:5]
	global_load_dwordx2 v[240:241], v[94:95], off
	global_load_dwordx2 v[242:243], v[94:95], off offset:32
	global_load_dwordx2 v[246:247], v[94:95], off offset:96
	global_load_dwordx2 v[248:249], v[94:95], off offset:128
	global_load_dwordx2 v[250:251], v[94:95], off offset:160
	global_load_dwordx2 v[252:253], v[94:95], off offset:192
	global_load_dword v98, v[4:5], off
	ds_read_b128 v[12:15], v27
	v_lshl_add_u64 v[36:37], v[36:37], 0, s[34:35]
	v_lshl_add_u64 v[34:35], v[34:35], 0, s[34:35]
	v_lshl_add_u64 v[32:33], v[32:33], 0, s[34:35]
	v_lshl_add_u64 v[30:31], v[30:31], 0, s[34:35]
	v_lshl_add_u64 v[28:29], v[28:29], 0, s[34:35]
	s_waitcnt vmcnt(20)
	v_cvt_pk_bf16_f32 v184, v184, v185
	v_cvt_pk_bf16_f32 v185, v186, v187
	ds_write_b64 v148, v[184:185]
	global_load_dwordx2 v[186:187], v[94:95], off offset:224
	s_waitcnt vmcnt(20)
	v_cvt_pk_bf16_f32 v188, v188, v189
	v_cvt_pk_bf16_f32 v189, v190, v191
	ds_write_b64 v149, v[188:189]
	global_load_dwordx2 v[190:191], v[94:95], off offset:64
	s_waitcnt vmcnt(20)
	v_cvt_pk_bf16_f32 v192, v192, v193
	v_cvt_pk_bf16_f32 v193, v194, v195
	ds_write_b64 v148, v[192:193] offset:8704
	s_waitcnt vmcnt(19)
	v_cvt_pk_bf16_f32 v196, v196, v197
	v_cvt_pk_bf16_f32 v197, v198, v199
	ds_write_b64 v150, v[196:197]
	s_waitcnt vmcnt(18)
	v_cvt_pk_bf16_f32 v200, v200, v201
	v_cvt_pk_bf16_f32 v201, v202, v203
	ds_write_b64 v148, v[200:201] offset:17408
	s_waitcnt vmcnt(17)
	v_cvt_pk_bf16_f32 v204, v204, v205
	v_cvt_pk_bf16_f32 v205, v206, v207
	ds_write_b64 v151, v[204:205]
	s_waitcnt vmcnt(16)
	v_cvt_pk_bf16_f32 v208, v208, v209
	v_cvt_pk_bf16_f32 v209, v210, v211
	ds_write_b64 v148, v[208:209] offset:26112
	s_waitcnt vmcnt(15)
	v_cvt_pk_bf16_f32 v212, v212, v213
	v_cvt_pk_bf16_f32 v213, v214, v215
	ds_write_b64 v152, v[212:213]
	s_waitcnt vmcnt(9)
	s_waitcnt lgkmcnt(0)
	v_lshlrev_b32_e32 v8, 16, v216
	v_mul_f32_e32 v8, v12, v8
	v_mul_f32_e32 v8, v8, v232
	v_lshlrev_b32_e32 v9, 16, v220
	v_mul_f32_e32 v9, v13, v9
	v_mul_f32_e32 v9, v9, v232
	v_lshlrev_b32_e32 v10, 16, v224
	v_mul_f32_e32 v10, v14, v10
	v_mul_f32_e32 v10, v10, v232
	v_lshlrev_b32_e32 v11, 16, v228
	v_mul_f32_e32 v11, v15, v11
	v_mul_f32_e32 v11, v11, v232
	v_cvt_pk_bf16_f32 v8, v8, v9
	v_cvt_pk_bf16_f32 v9, v10, v11
	ds_write_b64 v26, v[8:9] offset:34816
	v_and_b32_e32 v8, 0xffff0000, v216
	v_mul_f32_e32 v8, v12, v8
	v_mul_f32_e32 v8, v8, v233
	v_and_b32_e32 v9, 0xffff0000, v220
	v_mul_f32_e32 v9, v13, v9
	v_mul_f32_e32 v9, v9, v233
	v_and_b32_e32 v10, 0xffff0000, v224
	v_mul_f32_e32 v10, v14, v10
	v_mul_f32_e32 v10, v10, v233
	v_and_b32_e32 v11, 0xffff0000, v228
	v_mul_f32_e32 v11, v15, v11
	v_mul_f32_e32 v11, v11, v233
	v_cvt_pk_bf16_f32 v8, v8, v9
	v_cvt_pk_bf16_f32 v9, v10, v11
	ds_write_b64 v26, v[8:9] offset:35088
	v_lshlrev_b32_e32 v8, 16, v217
	v_mul_f32_e32 v8, v12, v8
	v_mul_f32_e32 v8, v8, v234
	v_lshlrev_b32_e32 v9, 16, v221
	v_mul_f32_e32 v9, v13, v9
	v_mul_f32_e32 v9, v9, v234
	v_lshlrev_b32_e32 v10, 16, v225
	v_mul_f32_e32 v10, v14, v10
	v_mul_f32_e32 v10, v10, v234
	v_lshlrev_b32_e32 v11, 16, v229
	v_mul_f32_e32 v11, v15, v11
	v_mul_f32_e32 v11, v11, v234
	v_cvt_pk_bf16_f32 v8, v8, v9
	v_cvt_pk_bf16_f32 v9, v10, v11
	ds_write_b64 v26, v[8:9] offset:35360
	v_and_b32_e32 v8, 0xffff0000, v217
	v_mul_f32_e32 v8, v12, v8
	v_mul_f32_e32 v8, v8, v235
	v_and_b32_e32 v9, 0xffff0000, v221
	v_mul_f32_e32 v9, v13, v9
	v_mul_f32_e32 v9, v9, v235
	v_and_b32_e32 v10, 0xffff0000, v225
	v_mul_f32_e32 v10, v14, v10
	v_mul_f32_e32 v10, v10, v235
	v_and_b32_e32 v11, 0xffff0000, v229
	v_mul_f32_e32 v11, v15, v11
	v_mul_f32_e32 v11, v11, v235
	v_cvt_pk_bf16_f32 v8, v8, v9
	v_cvt_pk_bf16_f32 v9, v10, v11
	ds_write_b64 v26, v[8:9] offset:35632
	v_lshlrev_b32_e32 v8, 16, v218
	v_mul_f32_e32 v8, v12, v8
	v_mul_f32_e32 v8, v8, v236
	v_lshlrev_b32_e32 v9, 16, v222
	v_mul_f32_e32 v9, v13, v9
	v_mul_f32_e32 v9, v9, v236
	v_lshlrev_b32_e32 v10, 16, v226
	v_mul_f32_e32 v10, v14, v10
	v_mul_f32_e32 v10, v10, v236
	v_lshlrev_b32_e32 v11, 16, v230
	v_mul_f32_e32 v11, v15, v11
	v_mul_f32_e32 v11, v11, v236
	v_cvt_pk_bf16_f32 v8, v8, v9
	v_cvt_pk_bf16_f32 v9, v10, v11
; #define LAS __attribute__((address_space(3)))
; __device__ __forceinline__ unsigned cvt_pk_bf16(float lo, float hi) { unsigned r; asm volatile("v_cvt_pk_bf16_f32 %0, %1, %2" : "=v"(r) : "v"(lo), "v"(hi)); return r; }
; __device__ __forceinline__ float bfel(const u32x4& v, int c) { const unsigned w = (c >> 1) == 0 ? v.x : (c >> 1) == 1 ? v.y : (c >> 1) == 2 ? v.z : v.w; return (c & 1) ? bfhi(w) : bflo(w); }
; __device__ __forceinline__ void gmlp_unit(const Params& p, LAS unsigned char* lds, int unit) {
;     ...
;             for (int c = 0; c < 8; ++c) { const float f = bfel(v, c) * rs * gn[d8 + c]; vnT[(d8 + c) * 136 + q] = (bf16_t)(cvt_pk_bf16(f, 0.f) & 0xffffu); } }
;         __syncthreads();
;         f32x4 acc[8];
; #pragma unroll
;         for (int nb = 0; nb < 8; ++nb) acc[nb] = (f32x4){0.f, 0.f, 0.f, 0.f};
; #pragma unroll
;         for (int kk = 0; kk < 4; ++kk) { const bf16x8 a = *(const LAS bf16x8*)(Wt + (16 * wid + fr) * 136 + kk * 32 + fq * 8);
; #pragma unroll
;             for (int nb = 0; nb < 8; ++nb) { const bf16x8 bv = *(const LAS bf16x8*)(vnT + (nb * 16 + fr) * 136 + kk * 32 + fq * 8);
;                 acc[nb] = __builtin_amdgcn_mfma_f32_16x16x32_bf16(bv, a, acc[nb], 0, 0, 0); } }
	ds_write_b64 v26, v[8:9] offset:35904
	v_and_b32_e32 v8, 0xffff0000, v218
	v_mul_f32_e32 v8, v12, v8
	v_mul_f32_e32 v8, v8, v237
	v_and_b32_e32 v9, 0xffff0000, v222
	v_mul_f32_e32 v9, v13, v9
	v_mul_f32_e32 v9, v9, v237
	v_and_b32_e32 v10, 0xffff0000, v226
	v_mul_f32_e32 v10, v14, v10
	v_mul_f32_e32 v10, v10, v237
	v_and_b32_e32 v11, 0xffff0000, v230
	v_mul_f32_e32 v11, v15, v11
	v_mul_f32_e32 v11, v11, v237
	v_cvt_pk_bf16_f32 v8, v8, v9
	v_cvt_pk_bf16_f32 v9, v10, v11
	ds_write_b64 v26, v[8:9] offset:36176
	v_lshlrev_b32_e32 v8, 16, v219
	v_mul_f32_e32 v8, v12, v8
	v_mul_f32_e32 v8, v8, v238
	v_lshlrev_b32_e32 v9, 16, v223
	v_mul_f32_e32 v9, v13, v9
	v_mul_f32_e32 v9, v9, v238
	v_lshlrev_b32_e32 v10, 16, v227
	v_mul_f32_e32 v10, v14, v10
	v_mul_f32_e32 v10, v10, v238
	v_lshlrev_b32_e32 v11, 16, v231
	v_mul_f32_e32 v11, v15, v11
	v_mul_f32_e32 v11, v11, v238
	v_cvt_pk_bf16_f32 v8, v8, v9
	v_cvt_pk_bf16_f32 v9, v10, v11
	ds_write_b64 v26, v[8:9] offset:36448
	v_and_b32_e32 v8, 0xffff0000, v219
	v_mul_f32_e32 v8, v12, v8
	v_mul_f32_e32 v8, v8, v239
	v_and_b32_e32 v9, 0xffff0000, v223
	v_mul_f32_e32 v9, v13, v9
	v_mul_f32_e32 v9, v9, v239
	v_and_b32_e32 v10, 0xffff0000, v227
	v_mul_f32_e32 v10, v14, v10
	v_mul_f32_e32 v10, v10, v239
	v_and_b32_e32 v11, 0xffff0000, v231
	v_mul_f32_e32 v11, v15, v11
	v_mul_f32_e32 v11, v11, v239
	v_cvt_pk_bf16_f32 v8, v8, v9
	v_cvt_pk_bf16_f32 v9, v10, v11
	ds_write_b64 v26, v[8:9] offset:36720
	s_waitcnt lgkmcnt(0)
	s_barrier
	ds_read_b128 v[8:11], v154 offset:34816
	ds_read_b128 v[0:3], v139
	ds_read_b128 v[4:7], v139 offset:64
	ds_read_b128 v[12:15], v154 offset:34880
	s_waitcnt lgkmcnt(2)
	v_mfma_f32_16x16x32_bf16 v[8:11], v[8:11], v[0:3], 0
	ds_read_b128 v[38:41], v154 offset:39168
	ds_read_b128 v[42:45], v154 offset:39232
	ds_read_b128 v[46:49], v154 offset:43520
	ds_read_b128 v[50:53], v154 offset:43584
	ds_read_b128 v[54:57], v154 offset:47872
	ds_read_b128 v[58:61], v154 offset:47936
	s_waitcnt lgkmcnt(6)
	v_mfma_f32_16x16x32_bf16 v[86:89], v[12:15], v[4:7], v[8:11]
	ds_read_b128 v[62:65], v154 offset:52224
	ds_read_b128 v[66:69], v154 offset:52288
	ds_read_b128 v[70:73], v154 offset:56576
	ds_read_b128 v[74:77], v154 offset:56640
	s_nop 0
	s_nop 0
	s_nop 0
	s_nop 0
	s_nop 0
	ds_read_b128 v[78:81], v154 offset:60928
	ds_read_b128 v[82:85], v154 offset:60992
	s_nop 0
	s_nop 0
	s_waitcnt lgkmcnt(11)
	v_mfma_f32_16x16x32_bf16 v[38:41], v[38:41], v[0:3], 0
	s_waitcnt lgkmcnt(9)
	v_mfma_f32_16x16x32_bf16 v[46:49], v[46:49], v[0:3], 0
	s_waitcnt lgkmcnt(7)
	v_mfma_f32_16x16x32_bf16 v[54:57], v[54:57], v[0:3], 0
	s_waitcnt lgkmcnt(5)
	v_mfma_f32_16x16x32_bf16 v[62:65], v[62:65], v[0:3], 0
	s_waitcnt lgkmcnt(3)
	v_mfma_f32_16x16x32_bf16 v[70:73], v[70:73], v[0:3], 0
	v_mfma_f32_16x16x32_bf16 v[38:41], v[42:45], v[4:7], v[38:41]
	v_mfma_f32_16x16x32_bf16 v[42:45], v[50:53], v[4:7], v[46:49]
	v_mfma_f32_16x16x32_bf16 v[46:49], v[58:61], v[4:7], v[54:57]
	v_mfma_f32_16x16x32_bf16 v[50:53], v[66:69], v[4:7], v[62:65]
	ds_read_b128 v[58:61], v154 offset:34944
	s_nop 1
	ds_read_b128 v[62:65], v154 offset:39296
	s_waitcnt lgkmcnt(3)
	v_mfma_f32_16x16x32_bf16 v[78:81], v[78:81], v[0:3], 0
	v_mfma_f32_16x16x32_bf16 v[54:57], v[74:77], v[4:7], v[70:73]
	ds_read_b128 v[12:15], v139 offset:128
	ds_read_b128 v[8:11], v139 offset:192
	s_nop 0
	ds_read_b128 v[70:73], v154 offset:35008
	s_waitcnt lgkmcnt(2)
	v_mfma_f32_16x16x32_bf16 v[58:61], v[58:61], v[12:15], v[86:89]
	v_mfma_f32_16x16x32_bf16 v[66:69], v[82:85], v[4:7], v[78:81]
	ds_read_b128 v[74:77], v154 offset:43648
	s_nop 1
	ds_read_b128 v[78:81], v154 offset:39360
	v_mfma_f32_16x16x32_bf16 v[38:41], v[62:65], v[12:15], v[38:41]
	ds_read_b128 v[62:65], v154 offset:48000
	ds_read_b128 v[82:85], v154 offset:43712
	s_waitcnt lgkmcnt(4)
	v_mfma_f32_16x16x32_bf16 v[58:61], v[70:73], v[8:11], v[58:61]
	s_waitcnt vmcnt(0)
	v_lshlrev_b32_e32 v70, 16, v240
	s_waitcnt lgkmcnt(3)
	v_mfma_f32_16x16x32_bf16 v[42:45], v[74:77], v[12:15], v[42:45]
	ds_read_b128 v[74:77], v154 offset:52352
	ds_read_b128 v[86:89], v154 offset:48064
	s_nop 0
	s_nop 0
	v_add_f32_e32 v58, v58, v98
	v_and_b32_e32 v71, 0xffff0000, v240
	s_waitcnt lgkmcnt(3)
	v_mfma_f32_16x16x32_bf16 v[46:49], v[62:65], v[12:15], v[46:49]
	ds_read_b128 v[62:65], v154 offset:56704
	ds_read_b128 v[90:93], v154 offset:65280
	ds_read_b128 v[156:159], v154 offset:52416
	v_add_f32_e32 v59, v59, v98
	v_lshlrev_b32_e32 v72, 16, v241
	v_add_f32_e32 v60, v60, v98
	v_and_b32_e32 v73, 0xffff0000, v241
	v_add_f32_e32 v61, v61, v98
	s_waitcnt lgkmcnt(4)
	v_mfma_f32_16x16x32_bf16 v[50:53], v[74:77], v[12:15], v[50:53]
	ds_read_b128 v[74:77], v154 offset:65344
	ds_read_b128 v[160:163], v154 offset:61056
	ds_read_b128 v[164:167], v154 offset:56768
	v_mul_f32_e32 v58, v58, v70
	v_mul_f32_e32 v59, v59, v71
	s_waitcnt lgkmcnt(5)
; #define LAS __attribute__((address_space(3)))
; __device__ __forceinline__ unsigned cvt_pk_bf16(float lo, float hi) { unsigned r; asm volatile("v_cvt_pk_bf16_f32 %0, %1, %2" : "=v"(r) : "v"(lo), "v"(hi)); return r; }
; __device__ __forceinline__ float bflo(unsigned u) { return __uint_as_float(u << 16); }
; __device__ __forceinline__ float bfhi(unsigned u) { return __uint_as_float(u & 0xffff0000u); }
; __device__ __forceinline__ void gmlp_unit(const Params& p, LAS unsigned char* lds, int unit) {
;     ...
;         for (int kk = 0; kk < 4; ++kk) { const bf16x8 a = *(const LAS bf16x8*)(Wt + (16 * wid + fr) * 136 + kk * 32 + fq * 8);
; #pragma unroll
;             for (int nb = 0; nb < 8; ++nb) { const bf16x8 bv = *(const LAS bf16x8*)(vnT + (nb * 16 + fr) * 136 + kk * 32 + fq * 8);
;                 acc[nb] = __builtin_amdgcn_mfma_f32_16x16x32_bf16(bv, a, acc[nb], 0, 0, 0); } }
;         const int pp = 16 * wid + fr; const float bs = p.in[18][g * 128 + pp];
; #pragma unroll
;         for (int nb = 0; nb < 8; ++nb) { const int d = nb * 16 + fq * 4; const u32x2 uu = *(const u32x2*)(U + (size_t)(r0 + pp) * 1024 + g * 128 + d);
;             u32x2 o; o.x = cvt_pk_bf16(bflo(uu.x) * (acc[nb][0] + bs), bfhi(uu.x) * (acc[nb][1] + bs)); o.y = cvt_pk_bf16(bflo(uu.y) * (acc[nb][2] + bs), bfhi(uu.y) * (acc[nb][3] + bs));
;             *(u32x2*)(CAT + (size_t)(r0 + pp) * 2048 + 1024 + g * 128 + d) = o; }
;         __syncthreads();
	v_mfma_f32_16x16x32_bf16 v[54:57], v[62:65], v[12:15], v[54:57]
	ds_read_b128 v[62:65], v154 offset:61120
	ds_read_b128 v[168:171], v154 offset:65408
	ds_read_b128 v[172:175], v154 offset:65472
	v_mul_f32_e32 v60, v60, v72
	v_mul_f32_e32 v61, v61, v73
	v_cvt_pk_bf16_f32 v70, v58, v59
	v_cvt_pk_bf16_f32 v71, v60, v61
	s_nop 0
	v_mfma_f32_16x16x32_bf16 v[38:41], v[78:81], v[8:11], v[38:41]
	v_lshl_add_u64 v[136:137], v[16:17], 0, s[6:7]
	s_add_u32 s6, s6, 0x100
	s_addc_u32 s7, s7, 0
	s_waitcnt lgkmcnt(4)
	v_mfma_f32_16x16x32_bf16 v[58:61], v[160:163], v[12:15], v[66:69]
	s_add_u32 s4, s4, 0x200
	s_nop 1
	v_add_f32_e32 v38, v38, v98
	v_add_f32_e32 v39, v39, v98
	v_add_co_u32_e32 v66, vcc, s43, v136
	v_add_f32_e32 v40, v40, v98
	s_nop 0
	v_addc_co_u32_e32 v67, vcc, 0, v137, vcc
	v_add_f32_e32 v41, v41, v98
	global_store_dwordx2 v[66:67], v[70:71], off offset:2048
	v_mfma_f32_16x16x32_bf16 v[0:3], v[90:93], v[0:3], 0
	s_addc_u32 s5, s5, 0
	s_cmpk_eq_i32 s6, 0x800
	s_nop 0
	v_lshlrev_b32_e32 v68, 16, v242
	v_and_b32_e32 v69, 0xffff0000, v242
	v_lshlrev_b32_e32 v70, 16, v243
	v_and_b32_e32 v71, 0xffff0000, v243
	v_mul_f32_e32 v38, v38, v68
	v_mul_f32_e32 v39, v39, v69
	v_mul_f32_e32 v40, v40, v70
	v_mul_f32_e32 v41, v41, v71
	v_cvt_pk_bf16_f32 v68, v38, v39
	v_cvt_pk_bf16_f32 v69, v40, v41
	s_nop 0
	v_mfma_f32_16x16x32_bf16 v[38:41], v[82:85], v[8:11], v[42:45]
	global_store_dwordx2 v[66:67], v[68:69], off offset:2080
	v_mfma_f32_16x16x32_bf16 v[0:3], v[74:77], v[4:7], v[0:3]
	s_nop 0
	v_lshlrev_b32_e32 v42, 16, v190
	s_nop 3
	v_add_f32_e32 v38, v38, v98
	v_add_f32_e32 v39, v39, v98
	v_add_f32_e32 v40, v40, v98
	v_add_f32_e32 v41, v41, v98
	v_and_b32_e32 v43, 0xffff0000, v190
	v_lshlrev_b32_e32 v44, 16, v191
	v_and_b32_e32 v45, 0xffff0000, v191
	v_mul_f32_e32 v38, v38, v42
	v_mul_f32_e32 v39, v39, v43
	v_mul_f32_e32 v40, v40, v44
	v_mul_f32_e32 v41, v41, v45
	v_cvt_pk_bf16_f32 v42, v38, v39
	v_cvt_pk_bf16_f32 v43, v40, v41
	s_nop 0
	v_mfma_f32_16x16x32_bf16 v[38:41], v[86:89], v[8:11], v[46:49]
	global_store_dwordx2 v[66:67], v[42:43], off offset:2112
	s_nop 0
	v_lshlrev_b32_e32 v42, 16, v246
	s_nop 4
	v_add_f32_e32 v38, v38, v98
	v_add_f32_e32 v39, v39, v98
	v_add_f32_e32 v40, v40, v98
	v_add_f32_e32 v41, v41, v98
	v_and_b32_e32 v43, 0xffff0000, v246
	v_lshlrev_b32_e32 v44, 16, v247
	v_and_b32_e32 v45, 0xffff0000, v247
	v_mul_f32_e32 v38, v38, v42
	v_mul_f32_e32 v39, v39, v43
	v_mul_f32_e32 v40, v40, v44
	v_mul_f32_e32 v41, v41, v45
	v_cvt_pk_bf16_f32 v42, v38, v39
	v_cvt_pk_bf16_f32 v43, v40, v41
	s_nop 0
	v_mfma_f32_16x16x32_bf16 v[38:41], v[156:159], v[8:11], v[50:53]
	global_store_dwordx2 v[66:67], v[42:43], off offset:2144
	s_nop 0
	v_lshlrev_b32_e32 v42, 16, v248
	s_nop 4
	v_add_f32_e32 v38, v38, v98
	v_add_f32_e32 v39, v39, v98
	v_add_f32_e32 v40, v40, v98
	v_add_f32_e32 v41, v41, v98
	v_and_b32_e32 v43, 0xffff0000, v248
	v_lshlrev_b32_e32 v44, 16, v249
	v_and_b32_e32 v45, 0xffff0000, v249
	v_mul_f32_e32 v38, v38, v42
	v_mul_f32_e32 v39, v39, v43
	v_mul_f32_e32 v40, v40, v44
	v_mul_f32_e32 v41, v41, v45
	v_cvt_pk_bf16_f32 v42, v38, v39
	v_cvt_pk_bf16_f32 v43, v40, v41
	s_nop 0
	s_waitcnt lgkmcnt(3)
	v_mfma_f32_16x16x32_bf16 v[38:41], v[164:167], v[8:11], v[54:57]
	global_store_dwordx2 v[66:67], v[42:43], off offset:2176
	s_nop 0
	v_lshlrev_b32_e32 v42, 16, v250
	s_nop 4
	v_add_f32_e32 v38, v38, v98
	v_add_f32_e32 v39, v39, v98
	v_add_f32_e32 v40, v40, v98
	v_add_f32_e32 v41, v41, v98
	v_and_b32_e32 v43, 0xffff0000, v250
	v_lshlrev_b32_e32 v44, 16, v251
	v_and_b32_e32 v45, 0xffff0000, v251
	v_mul_f32_e32 v38, v38, v42
	v_mul_f32_e32 v39, v39, v43
	v_mul_f32_e32 v40, v40, v44
	v_mul_f32_e32 v41, v41, v45
	v_cvt_pk_bf16_f32 v42, v38, v39
	v_cvt_pk_bf16_f32 v43, v40, v41
	s_nop 0
	s_waitcnt lgkmcnt(2)
	v_mfma_f32_16x16x32_bf16 v[38:41], v[62:65], v[8:11], v[58:61]
	global_store_dwordx2 v[66:67], v[42:43], off offset:2208
	s_nop 0
	v_lshlrev_b32_e32 v42, 16, v252
	s_nop 4
	v_add_f32_e32 v38, v38, v98
	v_add_f32_e32 v39, v39, v98
	v_add_f32_e32 v40, v40, v98
	v_add_f32_e32 v41, v41, v98
	v_and_b32_e32 v43, 0xffff0000, v252
	v_lshlrev_b32_e32 v44, 16, v253
	v_and_b32_e32 v45, 0xffff0000, v253
	v_mul_f32_e32 v38, v38, v42
	v_mul_f32_e32 v39, v39, v43
	v_mul_f32_e32 v40, v40, v44
	v_mul_f32_e32 v41, v41, v45
	v_cvt_pk_bf16_f32 v38, v38, v39
	v_cvt_pk_bf16_f32 v39, v40, v41
	s_nop 0
	s_waitcnt lgkmcnt(1)
	v_mfma_f32_16x16x32_bf16 v[0:3], v[168:171], v[12:15], v[0:3]
	global_store_dwordx2 v[66:67], v[38:39], off offset:2240
	s_nop 0
	v_lshlrev_b32_e32 v4, 16, v186
	s_waitcnt lgkmcnt(0)
	v_mfma_f32_16x16x32_bf16 v[0:3], v[172:175], v[8:11], v[0:3]
	v_and_b32_e32 v5, 0xffff0000, v186
	v_lshlrev_b32_e32 v6, 16, v187
	v_and_b32_e32 v7, 0xffff0000, v187
	s_nop 4
	v_add_f32_e32 v0, v0, v98
	v_add_f32_e32 v1, v1, v98
	v_add_f32_e32 v2, v2, v98
	v_add_f32_e32 v3, v3, v98
	v_mul_f32_e32 v0, v0, v4
	v_mul_f32_e32 v1, v1, v5
	v_mul_f32_e32 v2, v2, v6
	v_mul_f32_e32 v3, v3, v7
	v_cvt_pk_bf16_f32 v0, v0, v1
	v_cvt_pk_bf16_f32 v1, v2, v3
	global_store_dwordx2 v[66:67], v[0:1], off offset:2272
	s_barrier
	s_cbranch_scc0 .LBB0_1335
	s_branch .LBB0_1283

; #define LAS __attribute__((address_space(3)))
; __device__ __forceinline__ void mout_phase(const Params& p, LAS unsigned char* lds) {
;     ...
;         { const float aj = fv[256 + j];
; #pragma unroll
;           for (int nb = 0; nb < 17; ++nb) acc[nb] = acc[nb] * aj; }
;         __syncthreads();
; #pragma unroll
;         for (int i = 0; i < 8; ++i) { const int idx = t + 512 * i; *(LAS u32x4*)(T + (idx >> 4) * 136 + (idx & 15) * 8) = vreg[i]; }
;         if (t < 256) { const int r = 256 + (t >> 4), c8 = (t & 15) * 8; const unsigned one = (r == 256) ? 0x3F803F80u : 0u; *(LAS u32x4*)(T + r * 136 + c8) = (u32x4){one, one, one, one}; }
;         const float einv = fv[384 + j];
;         { const int un = (u & 1) ? u - 1 + 2 * (int)gridDim.x : u + 1; if (un < 2048) mout_issue(p, un, kreg, qf, gg); }
;         __syncthreads();
; #pragma unroll
;         for (int kk = 0; kk < 4; ++kk) { const bf16x8 sf = *(const LAS bf16x8*)(sb + j * 136 + kk * 32 + fq * 8);
; #pragma unroll
;             for (int nb = 0; nb < 17; ++nb) { const bf16x8 vf = *(const LAS bf16x8*)(T + (nb * 16 + fr) * 136 + kk * 32 + fq * 8);
;                 acc[nb] = __builtin_amdgcn_mfma_f32_16x16x32_bf16(vf, sf, acc[nb], 0, 0, 0); } }
.LBB0_1510:
	v_pk_mul_f32 v[102:103], v[62:63], v[138:139] op_sel_hi:[1,0]
	v_pk_mul_f32 v[100:101], v[60:61], v[138:139] op_sel_hi:[1,0]
	v_pk_mul_f32 v[98:99], v[66:67], v[138:139] op_sel_hi:[1,0]
	v_pk_mul_f32 v[96:97], v[64:65], v[138:139] op_sel_hi:[1,0]
	v_pk_mul_f32 v[66:67], v[74:75], v[138:139] op_sel_hi:[1,0]
	v_pk_mul_f32 v[64:65], v[72:73], v[138:139] op_sel_hi:[1,0]
	v_pk_mul_f32 v[62:63], v[78:79], v[138:139] op_sel_hi:[1,0]
	v_pk_mul_f32 v[60:61], v[76:77], v[138:139] op_sel_hi:[1,0]
	s_waitcnt lgkmcnt(0)
	s_barrier
	ds_read_b128 v[76:79], v200
	ds_read_b128 v[72:75], v201
	v_pk_mul_f32 v[126:127], v[38:39], v[138:139] op_sel_hi:[1,0]
	v_pk_mul_f32 v[124:125], v[36:37], v[138:139] op_sel_hi:[1,0]
	v_pk_mul_f32 v[114:115], v[50:51], v[138:139] op_sel_hi:[1,0]
	v_pk_mul_f32 v[112:113], v[48:49], v[138:139] op_sel_hi:[1,0]
	v_pk_mul_f32 v[50:51], v[90:91], v[138:139] op_sel_hi:[1,0]
	v_pk_mul_f32 v[48:49], v[88:89], v[138:139] op_sel_hi:[1,0]
	s_waitcnt lgkmcnt(0)
	v_mfma_f32_16x16x32_bf16 v[88:91], v[72:75], v[76:79], v[124:127]
	ds_read_b128 v[72:75], v201 offset:4352
	v_pk_mul_f32 v[122:123], v[42:43], v[138:139] op_sel_hi:[1,0]
	v_pk_mul_f32 v[120:121], v[40:41], v[138:139] op_sel_hi:[1,0]
	v_pk_mul_f32 v[118:119], v[46:47], v[138:139] op_sel_hi:[1,0]
	v_pk_mul_f32 v[116:117], v[44:45], v[138:139] op_sel_hi:[1,0]
	s_waitcnt lgkmcnt(0)
	v_mfma_f32_16x16x32_bf16 v[120:123], v[72:75], v[76:79], v[120:123]
	ds_read_b128 v[72:75], v201 offset:8704
	v_pk_mul_f32 v[110:111], v[54:55], v[138:139] op_sel_hi:[1,0]
	v_pk_mul_f32 v[108:109], v[52:53], v[138:139] op_sel_hi:[1,0]
	s_waitcnt lgkmcnt(0)
	v_mfma_f32_16x16x32_bf16 v[116:119], v[72:75], v[76:79], v[116:119]
	ds_read_b128 v[72:75], v201 offset:13056
	v_pk_mul_f32 v[106:107], v[58:59], v[138:139] op_sel_hi:[1,0]
	v_pk_mul_f32 v[104:105], v[56:57], v[138:139] op_sel_hi:[1,0]
	s_waitcnt lgkmcnt(0)
	v_mfma_f32_16x16x32_bf16 v[112:115], v[72:75], v[76:79], v[112:115]
	ds_read_b128 v[72:75], v201 offset:17408
	v_pk_mul_f32 v[46:47], v[94:95], v[138:139] op_sel_hi:[1,0]
	v_pk_mul_f32 v[44:45], v[92:93], v[138:139] op_sel_hi:[1,0]
	s_waitcnt lgkmcnt(0)
	v_mfma_f32_16x16x32_bf16 v[108:111], v[72:75], v[76:79], v[108:111]
	ds_read_b128 v[72:75], v201 offset:21760
	v_pk_mul_f32 v[58:59], v[82:83], v[138:139] op_sel_hi:[1,0]
	v_pk_mul_f32 v[56:57], v[80:81], v[138:139] op_sel_hi:[1,0]
	s_waitcnt lgkmcnt(0)
	v_mfma_f32_16x16x32_bf16 v[104:107], v[72:75], v[76:79], v[104:107]
	ds_read_b128 v[72:75], v201 offset:26112
	v_pk_mul_f32 v[70:71], v[70:71], v[138:139] op_sel_hi:[1,0]
	v_pk_mul_f32 v[68:69], v[68:69], v[138:139] op_sel_hi:[1,0]
	s_waitcnt lgkmcnt(0)
	v_mfma_f32_16x16x32_bf16 v[92:95], v[72:75], v[76:79], v[100:103]
	ds_read_b128 v[72:75], v201 offset:30464
	v_pk_mul_f32 v[54:55], v[86:87], v[138:139] op_sel_hi:[1,0]
	v_pk_mul_f32 v[52:53], v[84:85], v[138:139] op_sel_hi:[1,0]
	s_waitcnt lgkmcnt(0)
	v_mfma_f32_16x16x32_bf16 v[80:83], v[72:75], v[76:79], v[96:99]
	ds_read_b128 v[72:75], v201 offset:34816
	v_pk_mul_f32 v[42:43], v[130:131], v[138:139] op_sel_hi:[1,0]
	v_pk_mul_f32 v[40:41], v[128:129], v[138:139] op_sel_hi:[1,0]
	s_waitcnt lgkmcnt(0)
	v_mfma_f32_16x16x32_bf16 v[72:75], v[72:75], v[76:79], v[68:71]
	s_nop 2
	ds_read_b128 v[68:71], v201 offset:39168
	v_pk_mul_f32 v[38:39], v[134:135], v[138:139] op_sel_hi:[1,0]
	v_pk_mul_f32 v[36:37], v[132:133], v[138:139] op_sel_hi:[1,0]
	s_waitcnt lgkmcnt(0)
	v_mfma_f32_16x16x32_bf16 v[64:67], v[68:71], v[76:79], v[64:67]
	ds_read_b128 v[68:71], v201 offset:43520
	s_lshl_b32 s70, s84, 9
	v_lshlrev_b32_e32 v138, 1, v136
	s_waitcnt lgkmcnt(0)
	v_mfma_f32_16x16x32_bf16 v[60:63], v[68:71], v[76:79], v[60:63]
	ds_read_b128 v[68:71], v201 offset:47872
	s_waitcnt lgkmcnt(0)
	v_mfma_f32_16x16x32_bf16 v[56:59], v[68:71], v[76:79], v[56:59]
	ds_read_b128 v[68:71], v201 offset:52224
	s_waitcnt lgkmcnt(0)
	v_mfma_f32_16x16x32_bf16 v[52:55], v[68:71], v[76:79], v[52:55]
	ds_read_b128 v[68:71], v201 offset:56576
	s_waitcnt lgkmcnt(0)
	v_mfma_f32_16x16x32_bf16 v[48:51], v[68:71], v[76:79], v[48:51]
	ds_read_b128 v[68:71], v201 offset:60928
	s_waitcnt lgkmcnt(0)
	v_mfma_f32_16x16x32_bf16 v[44:47], v[68:71], v[76:79], v[44:47]
	ds_read_b128 v[68:71], v201 offset:65280
	s_waitcnt lgkmcnt(0)
	v_mfma_f32_16x16x32_bf16 v[40:43], v[68:71], v[76:79], v[40:43]
	ds_read_b128 v[68:71], v212
	s_waitcnt lgkmcnt(0)
	v_mfma_f32_16x16x32_bf16 v[36:39], v[68:71], v[76:79], v[36:39]
	ds_read_b128 v[84:87], v200 offset:64
	ds_read_b128 v[68:71], v201 offset:64
	ds_read_b128 v[100:103], v201 offset:17472
	ds_read_b128 v[76:79], v201 offset:4416
	s_waitcnt lgkmcnt(1)
	v_mfma_f32_16x16x32_bf16 v[100:103], v[100:103], v[84:87], v[108:111]
	s_nop 2
	ds_read_b128 v[108:111], v201 offset:21824
	ds_read_b128 v[96:99], v201 offset:13120
	s_waitcnt lgkmcnt(1)
	v_mfma_f32_16x16x32_bf16 v[104:107], v[108:111], v[84:87], v[104:107]
	ds_read_b128 v[108:111], v201 offset:26176
	s_waitcnt lgkmcnt(0)
	v_mfma_f32_16x16x32_bf16 v[92:95], v[108:111], v[84:87], v[92:95]
	ds_read_b128 v[108:111], v201 offset:30528
	s_waitcnt lgkmcnt(0)
	v_mfma_f32_16x16x32_bf16 v[80:83], v[108:111], v[84:87], v[80:83]
	ds_read_b128 v[108:111], v201 offset:34880
	v_mfma_f32_16x16x32_bf16 v[68:71], v[68:71], v[84:87], v[88:91]
	s_nop 2
	ds_read_b128 v[88:91], v201 offset:8768
	s_waitcnt lgkmcnt(1)
	v_mfma_f32_16x16x32_bf16 v[72:75], v[108:111], v[84:87], v[72:75]
	ds_read_b128 v[108:111], v201 offset:39232
	s_waitcnt lgkmcnt(0)
	v_mfma_f32_16x16x32_bf16 v[64:67], v[108:111], v[84:87], v[64:67]
	ds_read_b128 v[108:111], v201 offset:43584
	s_waitcnt lgkmcnt(0)
; #define LAS __attribute__((address_space(3)))
; __device__ __forceinline__ void mout_phase(const Params& p, LAS unsigned char* lds) {
;     ...
;         for (int kk = 0; kk < 4; ++kk) { const bf16x8 sf = *(const LAS bf16x8*)(sb + j * 136 + kk * 32 + fq * 8);
; #pragma unroll
;             for (int nb = 0; nb < 17; ++nb) { const bf16x8 vf = *(const LAS bf16x8*)(T + (nb * 16 + fr) * 136 + kk * 32 + fq * 8);
;                 acc[nb] = __builtin_amdgcn_mfma_f32_16x16x32_bf16(vf, sf, acc[nb], 0, 0, 0); } }
;         const float nq = __shfl(acc[16][0], fr);
;         const float inv = 1.f / fmaxf(fabsf(nq), einv);
;         bf16_t* hd = (bf16_t*)(p.ws + WS_HDIR) + (size_t)(r0 + j) * 1024 + h * 256;
;         if (dir == 0) {
	v_mfma_f32_16x16x32_bf16 v[60:63], v[108:111], v[84:87], v[60:63]
	ds_read_b128 v[108:111], v201 offset:47936
	s_waitcnt lgkmcnt(0)
	v_mfma_f32_16x16x32_bf16 v[56:59], v[108:111], v[84:87], v[56:59]
	ds_read_b128 v[108:111], v201 offset:52288
	s_waitcnt lgkmcnt(0)
	v_mfma_f32_16x16x32_bf16 v[52:55], v[108:111], v[84:87], v[52:55]
	ds_read_b128 v[108:111], v201 offset:56640
	s_waitcnt lgkmcnt(0)
	v_mfma_f32_16x16x32_bf16 v[48:51], v[108:111], v[84:87], v[48:51]
	ds_read_b128 v[108:111], v201 offset:60992
	s_waitcnt lgkmcnt(0)
	v_mfma_f32_16x16x32_bf16 v[44:47], v[108:111], v[84:87], v[44:47]
	ds_read_b128 v[108:111], v201 offset:65344
	s_waitcnt lgkmcnt(0)
	v_mfma_f32_16x16x32_bf16 v[40:43], v[108:111], v[84:87], v[40:43]
	ds_read_b128 v[108:111], v212 offset:64
	v_mfma_f32_16x16x32_bf16 v[76:79], v[76:79], v[84:87], v[120:123]
	v_mfma_f32_16x16x32_bf16 v[88:91], v[88:91], v[84:87], v[116:119]
	v_mfma_f32_16x16x32_bf16 v[96:99], v[96:99], v[84:87], v[112:115]
	s_waitcnt lgkmcnt(0)
	v_mfma_f32_16x16x32_bf16 v[36:39], v[108:111], v[84:87], v[36:39]
	ds_read_b128 v[84:87], v200 offset:128
	ds_read_b128 v[108:111], v201 offset:128
	s_waitcnt lgkmcnt(0)
	v_mfma_f32_16x16x32_bf16 v[108:111], v[108:111], v[84:87], v[68:71]
	s_nop 2
	ds_read_b128 v[68:71], v201 offset:4480
	s_waitcnt lgkmcnt(0)
	v_mfma_f32_16x16x32_bf16 v[76:79], v[68:71], v[84:87], v[76:79]
	ds_read_b128 v[68:71], v201 offset:8832
	s_waitcnt lgkmcnt(0)
	v_mfma_f32_16x16x32_bf16 v[88:91], v[68:71], v[84:87], v[88:91]
	ds_read_b128 v[68:71], v201 offset:13184
	s_waitcnt lgkmcnt(0)
	v_mfma_f32_16x16x32_bf16 v[96:99], v[68:71], v[84:87], v[96:99]
	ds_read_b128 v[68:71], v201 offset:17536
	s_waitcnt lgkmcnt(0)
	v_mfma_f32_16x16x32_bf16 v[112:115], v[68:71], v[84:87], v[100:103]
	ds_read_b128 v[68:71], v201 offset:21888
	s_waitcnt lgkmcnt(0)
	v_mfma_f32_16x16x32_bf16 v[104:107], v[68:71], v[84:87], v[104:107]
	ds_read_b128 v[68:71], v201 offset:26240
	s_waitcnt lgkmcnt(0)
	v_mfma_f32_16x16x32_bf16 v[116:119], v[68:71], v[84:87], v[92:95]
	ds_read_b128 v[68:71], v201 offset:30592
	s_waitcnt lgkmcnt(0)
	v_mfma_f32_16x16x32_bf16 v[80:83], v[68:71], v[84:87], v[80:83]
	ds_read_b128 v[68:71], v201 offset:34944
	s_waitcnt lgkmcnt(0)
	v_mfma_f32_16x16x32_bf16 v[72:75], v[68:71], v[84:87], v[72:75]
	ds_read_b128 v[68:71], v201 offset:39296
	s_waitcnt lgkmcnt(0)
	v_mfma_f32_16x16x32_bf16 v[120:123], v[68:71], v[84:87], v[64:67]
	s_nop 2
	ds_read_b128 v[64:67], v201 offset:43648
	s_waitcnt lgkmcnt(0)
	v_mfma_f32_16x16x32_bf16 v[68:71], v[64:67], v[84:87], v[60:63]
	s_nop 2
	ds_read_b128 v[60:63], v201 offset:48000
	s_waitcnt lgkmcnt(0)
	v_mfma_f32_16x16x32_bf16 v[64:67], v[60:63], v[84:87], v[56:59]
	s_nop 2
	ds_read_b128 v[56:59], v201 offset:52352
	s_waitcnt lgkmcnt(0)
	v_mfma_f32_16x16x32_bf16 v[60:63], v[56:59], v[84:87], v[52:55]
	s_nop 2
	ds_read_b128 v[52:55], v201 offset:56704
	s_waitcnt lgkmcnt(0)
	v_mfma_f32_16x16x32_bf16 v[52:55], v[52:55], v[84:87], v[48:51]
	s_nop 2
	ds_read_b128 v[48:51], v201 offset:61056
	s_waitcnt lgkmcnt(0)
	v_mfma_f32_16x16x32_bf16 v[48:51], v[48:51], v[84:87], v[44:47]
	s_nop 2
	ds_read_b128 v[44:47], v201 offset:65408
	s_waitcnt lgkmcnt(0)
	v_mfma_f32_16x16x32_bf16 v[44:47], v[44:47], v[84:87], v[40:43]
	s_nop 2
	ds_read_b128 v[40:43], v212 offset:128
	s_waitcnt lgkmcnt(0)
	v_mfma_f32_16x16x32_bf16 v[100:103], v[40:43], v[84:87], v[36:39]
	ds_read_b128 v[124:127], v200 offset:192
	s_nop 1
	ds_read_b128 v[36:39], v201 offset:192
	ds_read_b128 v[40:43], v201 offset:4544
	ds_read_b128 v[56:59], v201 offset:8896
	s_waitcnt lgkmcnt(1)
	v_mfma_f32_16x16x32_bf16 v[40:43], v[40:43], v[124:127], v[76:79]
	s_nop 2
	ds_read_b128 v[76:79], v201 offset:13248
	ds_read_b128 v[84:87], v201 offset:17600
	s_waitcnt lgkmcnt(1)
	v_mfma_f32_16x16x32_bf16 v[76:79], v[76:79], v[124:127], v[96:99]
	s_waitcnt lgkmcnt(0)
	v_mfma_f32_16x16x32_bf16 v[96:99], v[84:87], v[124:127], v[112:115]
	ds_read_b128 v[84:87], v201 offset:21952
	s_waitcnt lgkmcnt(0)
	v_mfma_f32_16x16x32_bf16 v[92:95], v[84:87], v[124:127], v[104:107]
	ds_read_b128 v[84:87], v201 offset:26304
	s_nop 1
	ds_read_b128 v[104:107], v201 offset:43712
	v_mfma_f32_16x16x32_bf16 v[56:59], v[56:59], v[124:127], v[88:91]
	s_waitcnt lgkmcnt(1)
	v_mfma_f32_16x16x32_bf16 v[88:91], v[84:87], v[124:127], v[116:119]
	ds_read_b128 v[84:87], v201 offset:30656
	s_waitcnt lgkmcnt(0)
	v_mfma_f32_16x16x32_bf16 v[84:87], v[84:87], v[124:127], v[80:83]
	s_nop 2
	ds_read_b128 v[80:83], v201 offset:35008
	s_waitcnt lgkmcnt(0)
	v_mfma_f32_16x16x32_bf16 v[80:83], v[80:83], v[124:127], v[72:75]
	s_nop 2
	ds_read_b128 v[72:75], v201 offset:39360
	v_mfma_f32_16x16x32_bf16 v[68:71], v[104:107], v[124:127], v[68:71]
	ds_read_b128 v[104:107], v201 offset:48064
	s_waitcnt lgkmcnt(0)
	v_mfma_f32_16x16x32_bf16 v[64:67], v[104:107], v[124:127], v[64:67]
	ds_read_b128 v[104:107], v201 offset:52416
	s_waitcnt lgkmcnt(0)
	v_mfma_f32_16x16x32_bf16 v[60:63], v[104:107], v[124:127], v[60:63]
	ds_read_b128 v[104:107], v201 offset:56768
	s_waitcnt lgkmcnt(0)
	v_mfma_f32_16x16x32_bf16 v[52:55], v[104:107], v[124:127], v[52:55]
	ds_read_b128 v[104:107], v201 offset:61120
	s_waitcnt lgkmcnt(0)
	v_mfma_f32_16x16x32_bf16 v[48:51], v[104:107], v[124:127], v[48:51]
	ds_read_b128 v[104:107], v201 offset:65472
	s_waitcnt lgkmcnt(0)
	v_mfma_f32_16x16x32_bf16 v[44:47], v[104:107], v[124:127], v[44:47]
	ds_read_b128 v[104:107], v212 offset:192
	s_waitcnt lgkmcnt(0)
	v_mfma_f32_16x16x32_bf16 v[100:103], v[104:107], v[124:127], v[100:103]
	v_lshl_add_u32 v106, s85, 7, v194
	s_nop 6
	v_and_or_b32 v101, v224, 64, v147
	v_lshlrev_b32_e32 v101, 2, v101
	ds_bpermute_b32 v100, v101, v100
	v_max_f32_e32 v101, v153, v153
	v_ashrrev_i32_e32 v107, 31, v106
	v_mfma_f32_16x16x32_bf16 v[36:39], v[36:39], v[124:127], v[108:111]
	s_waitcnt lgkmcnt(0)
	v_max_f32_e64 v100, |v100|, |v100|
	v_max_f32_e32 v100, v100, v101
	v_div_scale_f32 v101, s[80:81], v100, v100, 1.0
	v_rcp_f32_e32 v102, v101
	v_mfma_f32_16x16x32_bf16 v[72:75], v[72:75], v[124:127], v[120:123]
	s_mov_b64 s[80:81], -1
	v_fma_f32 v103, -v101, v102, 1.0
	v_fmac_f32_e32 v102, v103, v102
	v_div_scale_f32 v103, vcc, 1.0, v100, 1.0
	v_mul_f32_e32 v104, v103, v102
	v_fma_f32 v105, -v101, v104, v103
	v_fmac_f32_e32 v104, v105, v102
	v_fma_f32 v101, -v101, v104, v103
	v_div_fmas_f32 v101, v101, v102, v104
	v_lshlrev_b64 v[102:103], 11, v[106:107]
	v_lshl_add_u64 v[102:103], s[2:3], 0, v[102:103]
	v_lshl_add_u64 v[102:103], v[102:103], 0, s[70:71]
	v_div_fixup_f32 v100, v101, v100, 1.0
	v_lshl_add_u64 v[102:103], v[102:103], 0, v[138:139]
	s_and_b64 vcc, exec, s[66:67]
	s_cbranch_vccnz .LBB0_1512
; __device__ __forceinline__ float bflo(unsigned u) { return __uint_as_float(u << 16); }
; __device__ __forceinline__ float bfhi(unsigned u) { return __uint_as_float(u & 0xffff0000u); }
; __device__ __forceinline__ void mout_phase(const Params& p, LAS unsigned char* lds) {
;     ...
;             float ss = 0.f;
; #pragma unroll
;             for (int nb = 0; nb < 16; ++nb) { const u32x2 hv = *(const u32x2*)(hd + nb * 16 + 4 * fq);
;                 acc[nb][0] = acc[nb][0] * inv + bflo(hv.x); acc[nb][1] = acc[nb][1] * inv + bfhi(hv.x); acc[nb][2] = acc[nb][2] * inv + bflo(hv.y); acc[nb][3] = acc[nb][3] * inv + bfhi(hv.y);
;                 ss += acc[nb][0] * acc[nb][0] + acc[nb][1] * acc[nb][1] + acc[nb][2] * acc[nb][2] + acc[nb][3] * acc[nb][3]; }
	global_load_dwordx2 v[104:105], v[102:103], off
	global_load_dwordx2 v[110:111], v[102:103], off offset:32
	global_load_dwordx2 v[112:113], v[102:103], off offset:64
	global_load_dwordx2 v[114:115], v[102:103], off offset:96
	global_load_dwordx2 v[116:117], v[102:103], off offset:128
	global_load_dwordx2 v[118:119], v[102:103], off offset:160
	global_load_dwordx2 v[120:121], v[102:103], off offset:192
	global_load_dwordx2 v[122:123], v[102:103], off offset:224
	global_load_dwordx2 v[124:125], v[102:103], off offset:256
	global_load_dwordx2 v[130:131], v[102:103], off offset:288
	global_load_dwordx2 v[132:133], v[102:103], off offset:320
	global_load_dwordx2 v[134:135], v[102:103], off offset:352
	v_mov_b32_e32 v213, v244
	v_readlane_b32 s36, v255, 48
	v_lshlrev_b64 v[108:109], 10, v[106:107]
	v_readlane_b32 s37, v255, 49
	s_lshl_b32 s80, s84, 8
	v_lshlrev_b64 v[106:107], 12, v[106:107]
	v_lshl_add_u64 v[108:109], v[108:109], 1, s[36:37]
	v_readlane_b32 s36, v255, 50
	v_readlane_b32 s37, v255, 51
	s_lshl_b32 s70, s80, 1
	v_lshl_add_u64 v[108:109], v[108:109], 0, s[70:71]
	v_lshl_add_u64 v[106:107], s[36:37], 0, v[106:107]
	v_lshl_add_u64 v[108:109], v[108:109], 0, v[138:139]
	v_xor_b32_e32 v225, 16, v224
	s_waitcnt vmcnt(11)
	v_and_b32_e32 v163, 0xffff0000, v104
	s_waitcnt vmcnt(10)
	v_and_b32_e32 v171, 0xffff0000, v110
	v_lshlrev_b32_e32 v161, 16, v104
	v_lshlrev_b32_e32 v169, 16, v110
	s_waitcnt vmcnt(9)
	v_and_b32_e32 v236, 0xffff0000, v112
	v_fmac_f32_e32 v163, v37, v100
	v_fmac_f32_e32 v171, v41, v100
	v_lshlrev_b32_e32 v165, 16, v105
	v_and_b32_e32 v167, 0xffff0000, v105
	v_lshlrev_b32_e32 v173, 16, v111
	v_lshlrev_b32_e32 v177, 16, v112
	s_waitcnt vmcnt(8)
	v_and_b32_e32 v240, 0xffff0000, v114
	v_fmac_f32_e32 v161, v36, v100
	v_fmac_f32_e32 v169, v40, v100
	v_fmac_f32_e32 v236, v57, v100
	v_mul_f32_e32 v104, v163, v163
	v_mul_f32_e32 v105, v171, v171
	v_and_b32_e32 v175, 0xffff0000, v111
	v_lshlrev_b32_e32 v237, 16, v113
	v_lshlrev_b32_e32 v239, 16, v114
	s_waitcnt vmcnt(7)
	v_and_b32_e32 v244, 0xffff0000, v116
	v_fmac_f32_e32 v165, v38, v100
	v_fmac_f32_e32 v173, v42, v100
	v_fmac_f32_e32 v177, v56, v100
	v_fmac_f32_e32 v240, v77, v100
	v_mul_f32_e32 v110, v236, v236
	v_fmac_f32_e32 v104, v161, v161
	v_fmac_f32_e32 v105, v169, v169
	v_and_b32_e32 v238, 0xffff0000, v113
	v_lshlrev_b32_e32 v241, 16, v115
	v_lshlrev_b32_e32 v243, 16, v116
	s_waitcnt vmcnt(6)
	v_and_b32_e32 v155, 0xffff0000, v118
	v_fmac_f32_e32 v167, v39, v100
	v_fmac_f32_e32 v175, v43, v100
	v_fmac_f32_e32 v237, v58, v100
	v_fmac_f32_e32 v239, v76, v100
	v_fmac_f32_e32 v244, v97, v100
	v_mul_f32_e32 v111, v240, v240
	v_fmac_f32_e32 v110, v177, v177
	v_fmac_f32_e32 v104, v165, v165
	v_fmac_f32_e32 v105, v173, v173
	v_and_b32_e32 v242, 0xffff0000, v115
	v_lshlrev_b32_e32 v245, 16, v117
	v_lshlrev_b32_e32 v159, 16, v118
	v_fmac_f32_e32 v238, v59, v100
	v_fmac_f32_e32 v241, v78, v100
	v_fmac_f32_e32 v243, v96, v100
	v_fmac_f32_e32 v155, v93, v100
	v_mul_f32_e32 v112, v244, v244
	v_fmac_f32_e32 v111, v239, v239
	v_fmac_f32_e32 v110, v237, v237
	v_fmac_f32_e32 v104, v167, v167
	v_fmac_f32_e32 v105, v175, v175
	v_and_b32_e32 v246, 0xffff0000, v117
	v_lshlrev_b32_e32 v153, 16, v119
	v_fmac_f32_e32 v242, v79, v100
	v_fmac_f32_e32 v245, v98, v100
	v_fmac_f32_e32 v159, v92, v100
	v_mul_f32_e32 v113, v155, v155
	v_fmac_f32_e32 v112, v243, v243
	v_fmac_f32_e32 v111, v241, v241
	v_fmac_f32_e32 v110, v238, v238
	v_add_f32_e32 v104, v104, v105
	v_and_b32_e32 v101, 0xffff0000, v119
	v_fmac_f32_e32 v246, v99, v100
	v_fmac_f32_e32 v153, v94, v100
	v_fmac_f32_e32 v113, v159, v159
	v_fmac_f32_e32 v112, v245, v245
	v_fmac_f32_e32 v111, v242, v242
	v_add_f32_e32 v104, v104, v110
	v_fmac_f32_e32 v101, v95, v100
	v_fmac_f32_e32 v113, v153, v153
	v_fmac_f32_e32 v112, v246, v246
	v_add_f32_e32 v104, v104, v111
	v_fmac_f32_e32 v113, v101, v101
	v_add_f32_e32 v104, v104, v112
	v_add_f32_e32 v104, v104, v113
	global_load_dwordx2 v[110:111], v[102:103], off offset:384
	global_load_dwordx2 v[112:113], v[102:103], off offset:416
	global_load_dwordx2 v[116:117], v[102:103], off offset:448
	global_load_dwordx2 v[230:231], v[102:103], off offset:480
	s_waitcnt vmcnt(9)
	v_and_b32_e32 v248, 0xffff0000, v120
	v_lshlrev_b32_e32 v247, 16, v120
	v_fmac_f32_e32 v248, v89, v100
	v_fmac_f32_e32 v247, v88, v100
	v_lshlrev_b32_e32 v249, 16, v121
	v_mul_f32_e32 v105, v248, v248
	v_fmac_f32_e32 v249, v90, v100
	v_and_b32_e32 v250, 0xffff0000, v121
	v_fmac_f32_e32 v105, v247, v247
	v_fmac_f32_e32 v250, v91, v100
	v_fmac_f32_e32 v105, v249, v249
	s_waitcnt vmcnt(8)
	v_and_b32_e32 v252, 0xffff0000, v122
	v_fmac_f32_e32 v105, v250, v250
	v_lshlrev_b32_e32 v251, 16, v122
	v_fmac_f32_e32 v252, v85, v100
	v_add_f32_e32 v104, v104, v105
	v_fmac_f32_e32 v251, v84, v100
	v_lshlrev_b32_e32 v253, 16, v123
	v_mul_f32_e32 v105, v252, v252
	v_fmac_f32_e32 v253, v86, v100
	v_and_b32_e32 v141, 0xffff0000, v123
	v_fmac_f32_e32 v105, v251, v251
	v_fmac_f32_e32 v141, v87, v100
	v_fmac_f32_e32 v105, v253, v253
	v_fmac_f32_e32 v105, v141, v141
	v_add_f32_e32 v118, v104, v105
	v_mov_b32_e32 v104, v80
	v_mov_b32_e32 v105, v72
	s_waitcnt vmcnt(6)
	v_lshlrev_b32_e32 v115, 16, v130
	v_lshlrev_b32_e32 v114, 16, v124
	v_pk_fma_f32 v[126:127], v[104:105], v[100:101], v[114:115] op_sel_hi:[1,0,1]
	v_mov_b32_e32 v104, v81
	v_mov_b32_e32 v105, v73
	v_and_b32_e32 v115, 0xffff0000, v130
	v_and_b32_e32 v114, 0xffff0000, v124
	v_pk_fma_f32 v[128:129], v[104:105], v[100:101], v[114:115] op_sel_hi:[1,0,1]
	v_mov_b32_e32 v104, v82
	v_mov_b32_e32 v105, v74
	v_lshlrev_b32_e32 v115, 16, v131
	v_lshlrev_b32_e32 v114, 16, v125
	v_pk_fma_f32 v[180:181], v[104:105], v[100:101], v[114:115] op_sel_hi:[1,0,1]
	v_mov_b32_e32 v104, v83
	v_mov_b32_e32 v105, v75
	v_and_b32_e32 v115, 0xffff0000, v131
	v_and_b32_e32 v114, 0xffff0000, v125
	v_pk_fma_f32 v[182:183], v[104:105], v[100:101], v[114:115] op_sel_hi:[1,0,1]
	v_pk_mul_f32 v[104:105], v[128:129], v[128:129]
	s_waitcnt vmcnt(4)
; __device__ __forceinline__ void mout_phase(const Params& p, LAS unsigned char* lds) {
;     ...
;             ss += __shfl_xor(ss, 16); ss += __shfl_xor(ss, 32);
;             const float rstd = rsqrtf(ss * (1.f / 256.f) + 1e-6f);
;             const float* ng = p.in[15] + h * 256;
;             const bf16_t* og = (const bf16_t*)(p.ws + WS_O) + (size_t)(r0 + j) * 1024 + h * 256;
;             bf16_t* cat = (bf16_t*)(p.ws + WS_CAT) + (size_t)(r0 + j) * 2048 + h * 256;
; #pragma unroll
;             for (int nb = 0; nb < 16; ++nb) { const int dv = nb * 16 + 4 * fq; const f32x4 gn = *(const f32x4*)(ng + dv); const u32x2 ov = *(const u32x2*)(og + dv);
	v_lshlrev_b32_e32 v115, 16, v134
	v_pk_fma_f32 v[104:105], v[126:127], v[126:127], v[104:105]
	v_lshlrev_b32_e32 v114, 16, v132
	v_pk_fma_f32 v[104:105], v[180:181], v[180:181], v[104:105]
	global_load_dwordx2 v[232:233], v[108:109], off
	v_pk_fma_f32 v[104:105], v[182:183], v[182:183], v[104:105]
	s_waitcnt vmcnt(2)
	v_lshlrev_b32_e32 v234, 16, v117
	v_add_f32_e32 v104, v118, v104
	v_add_f32_e32 v130, v104, v105
	v_mov_b32_e32 v104, v68
	v_mov_b32_e32 v105, v64
	v_pk_fma_f32 v[118:119], v[104:105], v[100:101], v[114:115] op_sel_hi:[1,0,1]
	v_mov_b32_e32 v104, v69
	v_mov_b32_e32 v105, v65
	v_and_b32_e32 v115, 0xffff0000, v134
	v_and_b32_e32 v114, 0xffff0000, v132
	v_pk_fma_f32 v[120:121], v[104:105], v[100:101], v[114:115] op_sel_hi:[1,0,1]
	v_mov_b32_e32 v104, v70
	v_mov_b32_e32 v105, v66
	v_lshlrev_b32_e32 v115, 16, v135
	v_lshlrev_b32_e32 v114, 16, v133
	v_pk_fma_f32 v[122:123], v[104:105], v[100:101], v[114:115] op_sel_hi:[1,0,1]
	v_mov_b32_e32 v104, v71
	v_mov_b32_e32 v105, v67
	v_and_b32_e32 v115, 0xffff0000, v135
	v_and_b32_e32 v114, 0xffff0000, v133
	v_pk_fma_f32 v[124:125], v[104:105], v[100:101], v[114:115] op_sel_hi:[1,0,1]
	v_pk_mul_f32 v[104:105], v[120:121], v[120:121]
	v_lshlrev_b32_e32 v115, 16, v112
	v_pk_fma_f32 v[104:105], v[118:119], v[118:119], v[104:105]
	v_lshlrev_b32_e32 v114, 16, v110
	v_pk_fma_f32 v[104:105], v[122:123], v[122:123], v[104:105]
	v_and_b32_e32 v133, 0xffff0000, v112
	v_pk_fma_f32 v[104:105], v[124:125], v[124:125], v[104:105]
	v_and_b32_e32 v132, 0xffff0000, v110
	v_add_f32_e32 v104, v130, v104
	v_lshl_add_u64 v[130:131], v[106:107], 0, s[70:71]
	s_lshl_b32 s70, s80, 2
	v_lshl_add_u64 v[106:107], v[150:151], 0, s[70:71]
	global_load_dwordx4 v[226:229], v[106:107], off
	v_add_f32_e32 v157, v104, v105
	v_mov_b32_e32 v104, v60
	v_mov_b32_e32 v105, v52
	v_pk_fma_f32 v[104:105], v[104:105], v[100:101], v[114:115] op_sel_hi:[1,0,1]
	v_mov_b32_e32 v114, v61
	v_mov_b32_e32 v115, v53
	v_pk_fma_f32 v[132:133], v[114:115], v[100:101], v[132:133] op_sel_hi:[1,0,1]
	v_mov_b32_e32 v114, v62
	v_mov_b32_e32 v115, v54
	v_lshlrev_b32_e32 v135, 16, v113
	v_lshlrev_b32_e32 v134, 16, v111
	v_and_b32_e32 v112, 0xffff0000, v111
	v_pk_mul_f32 v[110:111], v[132:133], v[132:133]
	v_pk_fma_f32 v[134:135], v[114:115], v[100:101], v[134:135] op_sel_hi:[1,0,1]
	v_mov_b32_e32 v114, v63
	v_mov_b32_e32 v115, v55
	v_and_b32_e32 v113, 0xffff0000, v113
	v_pk_fma_f32 v[110:111], v[104:105], v[104:105], v[110:111]
	v_pk_fma_f32 v[178:179], v[114:115], v[100:101], v[112:113] op_sel_hi:[1,0,1]
	v_pk_fma_f32 v[110:111], v[134:135], v[134:135], v[110:111]
	s_waitcnt vmcnt(2)
	v_lshlrev_b32_e32 v113, 16, v230
	v_pk_fma_f32 v[110:111], v[178:179], v[178:179], v[110:111]
	v_lshlrev_b32_e32 v112, 16, v116
	v_add_f32_e32 v110, v157, v110
	v_add_f32_e32 v157, v110, v111
	v_mov_b32_e32 v110, v48
	v_mov_b32_e32 v111, v44
	v_pk_fma_f32 v[110:111], v[110:111], v[100:101], v[112:113] op_sel_hi:[1,0,1]
	v_mov_b32_e32 v112, v49
	v_mov_b32_e32 v113, v45
	v_and_b32_e32 v115, 0xffff0000, v230
	v_and_b32_e32 v114, 0xffff0000, v116
	v_pk_fma_f32 v[112:113], v[112:113], v[100:101], v[114:115] op_sel_hi:[1,0,1]
	v_mov_b32_e32 v114, v50
	v_mov_b32_e32 v115, v46
	v_lshlrev_b32_e32 v235, 16, v231
	v_pk_fma_f32 v[114:115], v[114:115], v[100:101], v[234:235] op_sel_hi:[1,0,1]
	v_mov_b32_e32 v234, v51
	v_mov_b32_e32 v235, v47
	v_and_b32_e32 v231, 0xffff0000, v231
	v_and_b32_e32 v230, 0xffff0000, v117
	v_pk_fma_f32 v[116:117], v[234:235], v[100:101], v[230:231] op_sel_hi:[1,0,1]
	v_pk_mul_f32 v[230:231], v[112:113], v[112:113]
	s_mov_b32 s70, 0x800000
	v_pk_fma_f32 v[230:231], v[110:111], v[110:111], v[230:231]
	v_lshl_add_u64 v[130:131], v[130:131], 0, v[138:139]
	v_pk_fma_f32 v[230:231], v[114:115], v[114:115], v[230:231]
	s_mov_b64 s[80:81], 0
	v_pk_fma_f32 v[230:231], v[116:117], v[116:117], v[230:231]
	s_nop 0
	v_add_f32_e32 v157, v157, v230
	v_and_b32_e32 v230, 64, v224
	v_add_u32_e32 v230, 64, v230
	v_cmp_lt_i32_e32 vcc, v225, v230
	v_add_f32_e32 v157, v157, v231
	s_nop 0
	v_cndmask_b32_e32 v225, v224, v225, vcc
	v_lshlrev_b32_e32 v225, 2, v225
	ds_bpermute_b32 v225, v225, v157
	s_waitcnt lgkmcnt(0)
	v_add_f32_e32 v157, v157, v225
	v_xor_b32_e32 v225, 32, v224
	v_cmp_lt_i32_e32 vcc, v225, v230
	s_nop 1
	v_cndmask_b32_e32 v224, v224, v225, vcc
	v_lshlrev_b32_e32 v224, 2, v224
	ds_bpermute_b32 v224, v224, v157
	s_waitcnt lgkmcnt(0)
	v_add_f32_e32 v157, v157, v224
	v_mov_b32_e32 v224, 0x358637bd
	v_fmamk_f32 v157, v157, 0x3b800000, v224
	v_mul_f32_e32 v224, 0x4b800000, v157
	v_cmp_gt_f32_e32 vcc, s70, v157
	s_nop 1
	v_cndmask_b32_e32 v157, v157, v224, vcc
	v_rsq_f32_e32 v157, v157
	s_nop 0
	v_mul_f32_e32 v224, 0x45800000, v157
	v_cndmask_b32_e32 v157, v157, v224, vcc
	global_load_dwordx2 v[36:37], v[108:109], off offset:32
	global_load_dwordx2 v[38:39], v[108:109], off offset:64
	global_load_dwordx2 v[40:41], v[108:109], off offset:96
	global_load_dwordx2 v[42:43], v[108:109], off offset:128
	global_load_dwordx2 v[44:45], v[108:109], off offset:160
	global_load_dwordx2 v[46:47], v[108:109], off offset:192
	global_load_dwordx2 v[48:49], v[108:109], off offset:224
	global_load_dwordx2 v[50:51], v[108:109], off offset:256
	global_load_dwordx2 v[52:53], v[108:109], off offset:288
	global_load_dwordx2 v[54:55], v[108:109], off offset:320
	global_load_dwordx2 v[56:57], v[108:109], off offset:352
	global_load_dwordx2 v[58:59], v[108:109], off offset:384
	global_load_dwordx2 v[60:61], v[108:109], off offset:416
	global_load_dwordx2 v[62:63], v[108:109], off offset:448
	global_load_dwordx2 v[64:65], v[108:109], off offset:480
	global_load_dwordx4 v[68:71], v[106:107], off offset:64
	global_load_dwordx4 v[72:75], v[106:107], off offset:128
	global_load_dwordx4 v[76:79], v[106:107], off offset:192
	global_load_dwordx4 v[80:83], v[106:107], off offset:256
	global_load_dwordx4 v[84:87], v[106:107], off offset:320
	global_load_dwordx4 v[88:91], v[106:107], off offset:384
	global_load_dwordx4 v[92:95], v[106:107], off offset:448
	global_load_dwordx4 v[96:99], v[106:107], off offset:512
	s_waitcnt vmcnt(23)
; __device__ __forceinline__ unsigned cvt_pk_bf16(float lo, float hi) { unsigned r; asm volatile("v_cvt_pk_bf16_f32 %0, %1, %2" : "=v"(r) : "v"(lo), "v"(hi)); return r; }
; __device__ __forceinline__ float bflo(unsigned u) { return __uint_as_float(u << 16); }
; __device__ __forceinline__ float bfhi(unsigned u) { return __uint_as_float(u & 0xffff0000u); }
; __device__ __forceinline__ void mout_phase(const Params& p, LAS unsigned char* lds) {
;     ...
; #pragma unroll
;             for (int nb = 0; nb < 16; ++nb) { const int dv = nb * 16 + 4 * fq; const f32x4 gn = *(const f32x4*)(ng + dv); const u32x2 ov = *(const u32x2*)(og + dv);
;                 u32x2 o; o.x = cvt_pk_bf16(acc[nb][0] * rstd * gn[0] * bflo(ov.x), acc[nb][1] * rstd * gn[1] * bfhi(ov.x));
;                 o.y = cvt_pk_bf16(acc[nb][2] * rstd * gn[2] * bflo(ov.y), acc[nb][3] * rstd * gn[3] * bfhi(ov.y));
;                 *(u32x2*)(cat + dv) = o;
;                 if ((nb & 3) == 3) asm volatile("" ::: "memory"); }
	v_mul_f32_e32 v161, v161, v157
	v_mul_f32_e32 v161, v161, v226
	v_lshlrev_b32_e32 v230, 16, v232
	v_mul_f32_e32 v161, v161, v230
	v_mul_f32_e32 v163, v163, v157
	v_mul_f32_e32 v163, v163, v227
	v_and_b32_e32 v230, 0xffff0000, v232
	v_mul_f32_e32 v163, v163, v230
	v_mul_f32_e32 v165, v165, v157
	v_mul_f32_e32 v165, v165, v228
	v_lshlrev_b32_e32 v230, 16, v233
	v_mul_f32_e32 v165, v165, v230
	v_mul_f32_e32 v167, v167, v157
	v_mul_f32_e32 v167, v167, v229
	v_and_b32_e32 v230, 0xffff0000, v233
	v_mul_f32_e32 v167, v167, v230
	v_cvt_pk_bf16_f32 v224, v161, v163
	v_cvt_pk_bf16_f32 v225, v165, v167
	global_store_dwordx2 v[130:131], v[224:225], off
	s_waitcnt vmcnt(8)
	v_mul_f32_e32 v169, v169, v157
	v_mul_f32_e32 v169, v169, v68
	v_lshlrev_b32_e32 v230, 16, v36
	v_mul_f32_e32 v169, v169, v230
	v_mul_f32_e32 v171, v171, v157
	v_mul_f32_e32 v171, v171, v69
	v_and_b32_e32 v230, 0xffff0000, v36
	v_mul_f32_e32 v171, v171, v230
	v_mul_f32_e32 v173, v173, v157
	v_mul_f32_e32 v173, v173, v70
	v_lshlrev_b32_e32 v230, 16, v37
	v_mul_f32_e32 v173, v173, v230
	v_mul_f32_e32 v175, v175, v157
	v_mul_f32_e32 v175, v175, v71
	v_and_b32_e32 v230, 0xffff0000, v37
	v_mul_f32_e32 v175, v175, v230
	v_cvt_pk_bf16_f32 v224, v169, v171
	v_cvt_pk_bf16_f32 v225, v173, v175
	global_store_dwordx2 v[130:131], v[224:225], off offset:32
	s_waitcnt vmcnt(8)
	v_mul_f32_e32 v177, v177, v157
	v_mul_f32_e32 v177, v177, v72
	v_lshlrev_b32_e32 v230, 16, v38
	v_mul_f32_e32 v177, v177, v230
	v_mul_f32_e32 v236, v236, v157
	v_mul_f32_e32 v236, v236, v73
	v_and_b32_e32 v230, 0xffff0000, v38
	v_mul_f32_e32 v236, v236, v230
	v_mul_f32_e32 v237, v237, v157
	v_mul_f32_e32 v237, v237, v74
	v_lshlrev_b32_e32 v230, 16, v39
	v_mul_f32_e32 v237, v237, v230
	v_mul_f32_e32 v238, v238, v157
	v_mul_f32_e32 v238, v238, v75
	v_and_b32_e32 v230, 0xffff0000, v39
	v_mul_f32_e32 v238, v238, v230
	v_cvt_pk_bf16_f32 v224, v177, v236
	v_cvt_pk_bf16_f32 v225, v237, v238
	global_store_dwordx2 v[130:131], v[224:225], off offset:64
	s_waitcnt vmcnt(8)
	v_mul_f32_e32 v239, v239, v157
	v_mul_f32_e32 v239, v239, v76
	v_lshlrev_b32_e32 v230, 16, v40
	v_mul_f32_e32 v239, v239, v230
	v_mul_f32_e32 v240, v240, v157
	v_mul_f32_e32 v240, v240, v77
	v_and_b32_e32 v230, 0xffff0000, v40
	v_mul_f32_e32 v240, v240, v230
	v_mul_f32_e32 v241, v241, v157
	v_mul_f32_e32 v241, v241, v78
	v_lshlrev_b32_e32 v230, 16, v41
	v_mul_f32_e32 v241, v241, v230
	v_mul_f32_e32 v242, v242, v157
	v_mul_f32_e32 v242, v242, v79
	v_and_b32_e32 v230, 0xffff0000, v41
	v_mul_f32_e32 v242, v242, v230
	v_cvt_pk_bf16_f32 v224, v239, v240
	v_cvt_pk_bf16_f32 v225, v241, v242
	global_store_dwordx2 v[130:131], v[224:225], off offset:96
	s_waitcnt vmcnt(8)
	v_mul_f32_e32 v243, v243, v157
	v_mul_f32_e32 v243, v243, v80
	v_lshlrev_b32_e32 v230, 16, v42
	v_mul_f32_e32 v243, v243, v230
	v_mul_f32_e32 v244, v244, v157
	v_mul_f32_e32 v244, v244, v81
	v_and_b32_e32 v230, 0xffff0000, v42
	v_mul_f32_e32 v244, v244, v230
	v_mul_f32_e32 v245, v245, v157
	v_mul_f32_e32 v245, v245, v82
	v_lshlrev_b32_e32 v230, 16, v43
	v_mul_f32_e32 v245, v245, v230
	v_mul_f32_e32 v246, v246, v157
	v_mul_f32_e32 v246, v246, v83
	v_and_b32_e32 v230, 0xffff0000, v43
	v_mul_f32_e32 v246, v246, v230
	v_cvt_pk_bf16_f32 v224, v243, v244
	v_cvt_pk_bf16_f32 v225, v245, v246
	global_store_dwordx2 v[130:131], v[224:225], off offset:128
	s_waitcnt vmcnt(8)
	v_mul_f32_e32 v159, v159, v157
	v_mul_f32_e32 v159, v159, v84
	v_lshlrev_b32_e32 v230, 16, v44
	v_mul_f32_e32 v159, v159, v230
	v_mul_f32_e32 v155, v155, v157
	v_mul_f32_e32 v155, v155, v85
	v_and_b32_e32 v230, 0xffff0000, v44
	v_mul_f32_e32 v155, v155, v230
	v_mul_f32_e32 v153, v153, v157
	v_mul_f32_e32 v153, v153, v86
	v_lshlrev_b32_e32 v230, 16, v45
	v_mul_f32_e32 v153, v153, v230
	v_mul_f32_e32 v101, v101, v157
	v_mul_f32_e32 v101, v101, v87
	v_and_b32_e32 v230, 0xffff0000, v45
	v_mul_f32_e32 v101, v101, v230
	v_cvt_pk_bf16_f32 v224, v159, v155
	v_cvt_pk_bf16_f32 v225, v153, v101
	global_store_dwordx2 v[130:131], v[224:225], off offset:160
	s_waitcnt vmcnt(8)
	v_mul_f32_e32 v247, v247, v157
	v_mul_f32_e32 v247, v247, v88
	v_lshlrev_b32_e32 v230, 16, v46
	v_mul_f32_e32 v247, v247, v230
	v_mul_f32_e32 v248, v248, v157
	v_mul_f32_e32 v248, v248, v89
	v_and_b32_e32 v230, 0xffff0000, v46
	v_mul_f32_e32 v248, v248, v230
	v_mul_f32_e32 v249, v249, v157
	v_mul_f32_e32 v249, v249, v90
	v_lshlrev_b32_e32 v230, 16, v47
	v_mul_f32_e32 v249, v249, v230
	v_mul_f32_e32 v250, v250, v157
	v_mul_f32_e32 v250, v250, v91
	v_and_b32_e32 v230, 0xffff0000, v47
	v_mul_f32_e32 v250, v250, v230
	v_cvt_pk_bf16_f32 v224, v247, v248
	v_cvt_pk_bf16_f32 v225, v249, v250
	global_store_dwordx2 v[130:131], v[224:225], off offset:192
	s_waitcnt vmcnt(8)
	v_mul_f32_e32 v251, v251, v157
	v_mul_f32_e32 v251, v251, v92
	v_lshlrev_b32_e32 v230, 16, v48
	v_mul_f32_e32 v251, v251, v230
	v_mul_f32_e32 v252, v252, v157
	v_mul_f32_e32 v252, v252, v93
	v_and_b32_e32 v230, 0xffff0000, v48
	v_mul_f32_e32 v252, v252, v230
	v_mul_f32_e32 v253, v253, v157
	v_mul_f32_e32 v253, v253, v94
	v_lshlrev_b32_e32 v230, 16, v49
	v_mul_f32_e32 v253, v253, v230
	v_mul_f32_e32 v141, v141, v157
	v_mul_f32_e32 v141, v141, v95
	v_and_b32_e32 v230, 0xffff0000, v49
	v_mul_f32_e32 v141, v141, v230
	v_cvt_pk_bf16_f32 v224, v251, v252
	v_cvt_pk_bf16_f32 v225, v253, v141
	global_store_dwordx2 v[130:131], v[224:225], off offset:224
	s_waitcnt vmcnt(8)
; __device__ __forceinline__ unsigned cvt_pk_bf16(float lo, float hi) { unsigned r; asm volatile("v_cvt_pk_bf16_f32 %0, %1, %2" : "=v"(r) : "v"(lo), "v"(hi)); return r; }
; __device__ __forceinline__ float bflo(unsigned u) { return __uint_as_float(u << 16); }
; __device__ __forceinline__ float bfhi(unsigned u) { return __uint_as_float(u & 0xffff0000u); }
; __device__ __forceinline__ void mout_phase(const Params& p, LAS unsigned char* lds) {
;     ...
; #pragma unroll
;             for (int nb = 0; nb < 16; ++nb) { const int dv = nb * 16 + 4 * fq; const f32x4 gn = *(const f32x4*)(ng + dv); const u32x2 ov = *(const u32x2*)(og + dv);
;                 u32x2 o; o.x = cvt_pk_bf16(acc[nb][0] * rstd * gn[0] * bflo(ov.x), acc[nb][1] * rstd * gn[1] * bfhi(ov.x));
;                 o.y = cvt_pk_bf16(acc[nb][2] * rstd * gn[2] * bflo(ov.y), acc[nb][3] * rstd * gn[3] * bfhi(ov.y));
;                 *(u32x2*)(cat + dv) = o;
;                 if ((nb & 3) == 3) asm volatile("" ::: "memory"); }
	v_mul_f32_e32 v126, v126, v157
	v_mul_f32_e32 v126, v126, v96
	v_lshlrev_b32_e32 v230, 16, v50
	v_mul_f32_e32 v126, v126, v230
	v_mul_f32_e32 v128, v128, v157
	v_mul_f32_e32 v128, v128, v97
	v_and_b32_e32 v230, 0xffff0000, v50
	v_mul_f32_e32 v128, v128, v230
	v_mul_f32_e32 v180, v180, v157
	v_mul_f32_e32 v180, v180, v98
	v_lshlrev_b32_e32 v230, 16, v51
	v_mul_f32_e32 v180, v180, v230
	v_mul_f32_e32 v182, v182, v157
	v_mul_f32_e32 v182, v182, v99
	v_and_b32_e32 v230, 0xffff0000, v51
	v_mul_f32_e32 v182, v182, v230
	v_cvt_pk_bf16_f32 v224, v126, v128
	v_cvt_pk_bf16_f32 v225, v180, v182
	global_store_dwordx2 v[130:131], v[224:225], off offset:256
	global_load_dwordx4 v[68:71], v[106:107], off offset:576
	global_load_dwordx4 v[72:75], v[106:107], off offset:640
	global_load_dwordx4 v[76:79], v[106:107], off offset:704
	global_load_dwordx4 v[80:83], v[106:107], off offset:768
	global_load_dwordx4 v[84:87], v[106:107], off offset:832
	global_load_dwordx4 v[88:91], v[106:107], off offset:896
	global_load_dwordx4 v[92:95], v[106:107], off offset:960
	s_waitcnt vmcnt(6)
	v_mul_f32_e32 v127, v127, v157
	v_mul_f32_e32 v127, v127, v68
	v_lshlrev_b32_e32 v230, 16, v52
	v_mul_f32_e32 v127, v127, v230
	v_mul_f32_e32 v129, v129, v157
	v_mul_f32_e32 v129, v129, v69
	v_and_b32_e32 v230, 0xffff0000, v52
	v_mul_f32_e32 v129, v129, v230
	v_mul_f32_e32 v181, v181, v157
	v_mul_f32_e32 v181, v181, v70
	v_lshlrev_b32_e32 v230, 16, v53
	v_mul_f32_e32 v181, v181, v230
	v_mul_f32_e32 v183, v183, v157
	v_mul_f32_e32 v183, v183, v71
	v_and_b32_e32 v230, 0xffff0000, v53
	v_mul_f32_e32 v183, v183, v230
	v_cvt_pk_bf16_f32 v224, v127, v129
	v_cvt_pk_bf16_f32 v225, v181, v183
	global_store_dwordx2 v[130:131], v[224:225], off offset:288
	s_waitcnt vmcnt(6)
	v_mul_f32_e32 v118, v118, v157
	v_mul_f32_e32 v118, v118, v72
	v_lshlrev_b32_e32 v230, 16, v54
	v_mul_f32_e32 v118, v118, v230
	v_mul_f32_e32 v120, v120, v157
	v_mul_f32_e32 v120, v120, v73
	v_and_b32_e32 v230, 0xffff0000, v54
	v_mul_f32_e32 v120, v120, v230
	v_mul_f32_e32 v122, v122, v157
	v_mul_f32_e32 v122, v122, v74
	v_lshlrev_b32_e32 v230, 16, v55
	v_mul_f32_e32 v122, v122, v230
	v_mul_f32_e32 v124, v124, v157
	v_mul_f32_e32 v124, v124, v75
	v_and_b32_e32 v230, 0xffff0000, v55
	v_mul_f32_e32 v124, v124, v230
	v_cvt_pk_bf16_f32 v224, v118, v120
	v_cvt_pk_bf16_f32 v225, v122, v124
	global_store_dwordx2 v[130:131], v[224:225], off offset:320
	s_waitcnt vmcnt(6)
	v_mul_f32_e32 v119, v119, v157
	v_mul_f32_e32 v119, v119, v76
	v_lshlrev_b32_e32 v230, 16, v56
	v_mul_f32_e32 v119, v119, v230
	v_mul_f32_e32 v121, v121, v157
	v_mul_f32_e32 v121, v121, v77
	v_and_b32_e32 v230, 0xffff0000, v56
	v_mul_f32_e32 v121, v121, v230
	v_mul_f32_e32 v123, v123, v157
	v_mul_f32_e32 v123, v123, v78
	v_lshlrev_b32_e32 v230, 16, v57
	v_mul_f32_e32 v123, v123, v230
	v_mul_f32_e32 v125, v125, v157
	v_mul_f32_e32 v125, v125, v79
	v_and_b32_e32 v230, 0xffff0000, v57
	v_mul_f32_e32 v125, v125, v230
	v_cvt_pk_bf16_f32 v224, v119, v121
	v_cvt_pk_bf16_f32 v225, v123, v125
	global_store_dwordx2 v[130:131], v[224:225], off offset:352
	s_waitcnt vmcnt(6)
	v_mul_f32_e32 v104, v104, v157
	v_mul_f32_e32 v104, v104, v80
	v_lshlrev_b32_e32 v230, 16, v58
	v_mul_f32_e32 v104, v104, v230
	v_mul_f32_e32 v132, v132, v157
	v_mul_f32_e32 v132, v132, v81
	v_and_b32_e32 v230, 0xffff0000, v58
	v_mul_f32_e32 v132, v132, v230
	v_mul_f32_e32 v134, v134, v157
	v_mul_f32_e32 v134, v134, v82
	v_lshlrev_b32_e32 v230, 16, v59
	v_mul_f32_e32 v134, v134, v230
	v_mul_f32_e32 v178, v178, v157
	v_mul_f32_e32 v178, v178, v83
	v_and_b32_e32 v230, 0xffff0000, v59
	v_mul_f32_e32 v178, v178, v230
	v_cvt_pk_bf16_f32 v224, v104, v132
	v_cvt_pk_bf16_f32 v225, v134, v178
	global_store_dwordx2 v[130:131], v[224:225], off offset:384
	s_waitcnt vmcnt(6)
	v_mul_f32_e32 v105, v105, v157
	v_mul_f32_e32 v105, v105, v84
	v_lshlrev_b32_e32 v230, 16, v60
	v_mul_f32_e32 v105, v105, v230
	v_mul_f32_e32 v133, v133, v157
	v_mul_f32_e32 v133, v133, v85
	v_and_b32_e32 v230, 0xffff0000, v60
	v_mul_f32_e32 v133, v133, v230
	v_mul_f32_e32 v135, v135, v157
	v_mul_f32_e32 v135, v135, v86
	v_lshlrev_b32_e32 v230, 16, v61
	v_mul_f32_e32 v135, v135, v230
	v_mul_f32_e32 v179, v179, v157
	v_mul_f32_e32 v179, v179, v87
	v_and_b32_e32 v230, 0xffff0000, v61
	v_mul_f32_e32 v179, v179, v230
	v_cvt_pk_bf16_f32 v224, v105, v133
	v_cvt_pk_bf16_f32 v225, v135, v179
	global_store_dwordx2 v[130:131], v[224:225], off offset:416
	s_waitcnt vmcnt(6)
	v_mul_f32_e32 v110, v110, v157
	v_mul_f32_e32 v110, v110, v88
	v_lshlrev_b32_e32 v230, 16, v62
	v_mul_f32_e32 v110, v110, v230
	v_mul_f32_e32 v112, v112, v157
	v_mul_f32_e32 v112, v112, v89
	v_and_b32_e32 v230, 0xffff0000, v62
	v_mul_f32_e32 v112, v112, v230
	v_mul_f32_e32 v114, v114, v157
	v_mul_f32_e32 v114, v114, v90
	v_lshlrev_b32_e32 v230, 16, v63
	v_mul_f32_e32 v114, v114, v230
	v_mul_f32_e32 v116, v116, v157
	v_mul_f32_e32 v116, v116, v91
	v_and_b32_e32 v230, 0xffff0000, v63
	v_mul_f32_e32 v116, v116, v230
	v_cvt_pk_bf16_f32 v224, v110, v112
	v_cvt_pk_bf16_f32 v225, v114, v116
	global_store_dwordx2 v[130:131], v[224:225], off offset:448
	s_waitcnt vmcnt(6)
	v_mul_f32_e32 v111, v111, v157
	v_mul_f32_e32 v111, v111, v92
	v_lshlrev_b32_e32 v230, 16, v64
	v_mul_f32_e32 v111, v111, v230
	v_mul_f32_e32 v113, v113, v157
	v_mul_f32_e32 v113, v113, v93
	v_and_b32_e32 v230, 0xffff0000, v64
	v_mul_f32_e32 v113, v113, v230
	v_mul_f32_e32 v115, v115, v157
	v_mul_f32_e32 v115, v115, v94
	v_lshlrev_b32_e32 v230, 16, v65
	v_mul_f32_e32 v115, v115, v230
	v_mul_f32_e32 v117, v117, v157
	v_mul_f32_e32 v117, v117, v95
	v_and_b32_e32 v230, 0xffff0000, v65
	v_mul_f32_e32 v117, v117, v230
	v_cvt_pk_bf16_f32 v224, v111, v113
	v_cvt_pk_bf16_f32 v225, v115, v117
	global_store_dwordx2 v[130:131], v[224:225], off offset:480
	v_mov_b32_e32 v244, v213
